# FFN-in: A rows staged row-interleaved (lane holds 4 consecutive rows per half) so the causal conv runs along registers: 27 instead of 38 VALU per 8 values; slow select path for waves containing a sequ
# speedup vs baseline: 1.0006x; 1.0006x over previous
.LBB0_977:
	s_and_b64 vcc, exec, s[4:5]
	s_cbranch_vccnz .LBB0_1013
	v_ashrrev_i32_e32 v0, 31, v8
	v_lshrrev_b32_e32 v0, 26, v0
	v_add_u32_e32 v0, v8, v0
	v_ashrrev_i32_e32 v1, 6, v0
	v_bfe_i32 v0, v8, 27, 1
	v_lshlrev_b32_e32 v2, 4, v8
	v_lshrrev_b32_e32 v0, 22, v0
	v_add_u32_e32 v0, v2, v0
	v_and_b32_e32 v0, 0xfffffc00, v0
	v_sub_u32_e32 v0, v2, v0
	v_lshrrev_b32_e32 v3, 4, v0
	v_bitop3_b32 v3, v3, v0, 32 bitop3:0x6c
	v_ashrrev_i32_e32 v0, 31, v0
	v_lshrrev_b32_e32 v0, 26, v0
	v_lshlrev_b32_e32 v4, 3, v1
	v_add_u32_e32 v0, v3, v0
	v_and_b32_e32 v4, -16, v4
	v_ashrrev_i32_e32 v5, 6, v0
	v_lshlrev_b32_e32 v1, 5, v1
	v_add_u32_e32 v0, v5, v4
	v_and_b32_e32 v4, 32, v1
	v_mul_i32_i24_e32 v1, 64, v5
	v_sub_u32_e32 v1, v3, v1
	v_ashrrev_i16_sdwa v1, v196, sext(v1) dst_sel:DWORD dst_unused:UNUSED_PAD src0_sel:DWORD src1_sel:BYTE_0
	v_bfe_i32 v3, v1, 0, 16
	v_lshlrev_b32_e32 v1, 1, v0
	v_lshrrev_b32_e32 v6, 2, v0
	v_and_b32_e32 v5, 3, v5
	s_mov_b32 s6, 0x1fffe0
	v_and_b32_e32 v1, 24, v1
	v_and_b32_e32 v6, 4, v6
	v_and_or_b32 v5, v0, s6, v5
	v_or3_b32 v5, v5, v6, v1
	v_and_b32_e32 v250, 15, v0
	v_bfe_u32 v251, v0, 4, 2
	v_lshl_or_b32 v250, v250, 2, v251
	v_and_b32_e32 v0, 0xffffffc0, v0
	v_or_b32_e32 v0, v0, v250
	v_lshrrev_b32_e32 v1, 6, v0
	v_mad_u64_u32 v[0:1], s[4:5], v1, 62, v[0:1]
	v_add_lshl_u32 v1, v4, v3, 1
	v_lshl_add_u32 v172, v0, 11, v1
	v_add_u32_e32 v0, 0x2000, v2
	v_lshl_add_u32 v128, v5, 11, v1
	v_ashrrev_i32_e32 v1, 31, v0
	v_lshrrev_b32_e32 v1, 22, v1
	v_add_u32_e32 v1, v0, v1
	v_ashrrev_i32_e32 v1, 10, v1
	v_mul_i32_i24_e32 v2, 0x400, v1
	v_sub_u32_e32 v0, v0, v2
	v_lshrrev_b32_e32 v2, 4, v0
	v_bitop3_b32 v2, v2, v0, 32 bitop3:0x6c
	v_ashrrev_i32_e32 v3, 31, v2
	v_lshrrev_b32_e32 v3, 26, v3
	v_lshlrev_b32_e32 v0, 3, v1
	v_add_u32_e32 v3, v2, v3
	v_lshlrev_b32_e32 v1, 5, v1
	v_and_b32_e32 v5, 32, v1
	v_and_b32_e32 v1, 0xc0, v3
	v_and_b32_e32 v0, -16, v0
	v_ashrrev_i32_e32 v4, 6, v3
	v_sub_u32_e32 v1, v2, v1
	v_add_u32_e32 v0, v4, v0
	v_ashrrev_i16_sdwa v1, v196, sext(v1) dst_sel:DWORD dst_unused:UNUSED_PAD src0_sel:DWORD src1_sel:BYTE_0
	s_ashr_i32 s23, s22, 6
	v_bfe_i32 v2, v1, 0, 16
	v_lshlrev_b32_e32 v1, 1, v0
	v_lshrrev_b32_e32 v3, 2, v0
	v_and_b32_e32 v4, 3, v4
	v_and_b32_e32 v1, 24, v1
	v_and_b32_e32 v3, 4, v3
	v_and_or_b32 v4, v0, s6, v4
	s_lshl_b32 s39, s23, 10
	v_or3_b32 v3, v4, v3, v1
	v_and_b32_e32 v250, 15, v0
	v_bfe_u32 v251, v0, 4, 2
	v_lshl_or_b32 v250, v250, 2, v251
	v_and_b32_e32 v0, 0xffffffc0, v0
	v_or_b32_e32 v0, v0, v250
	v_lshrrev_b32_e32 v1, 6, v0
	s_add_i32 s44, s39, 0
	v_mad_u64_u32 v[0:1], s[4:5], v1, 62, v[0:1]
	s_add_i32 m0, s44, 0x10000
	v_add_lshl_u32 v1, v5, v2, 1
	s_ashr_i32 s24, s22, 8
	global_load_lds_dwordx4 v128, s[8:9]
	s_add_i32 m0, s44, 0x12000
	v_lshl_add_u32 v130, v3, 11, v1
	s_add_u32 s4, s8, 0x40000
	global_load_lds_dwordx4 v130, s[8:9]
	s_addc_u32 s5, s9, 0
	s_add_i32 m0, s44, 0x14000
	s_add_i32 s45, s44, 0x2000
	global_load_lds_dwordx4 v128, s[4:5]
	s_add_i32 m0, s44, 0x16000
	v_lshl_add_u32 v132, v0, 11, v1
	global_load_lds_dwordx4 v130, s[4:5]
	s_mov_b32 m0, s44
	s_add_u32 s4, s10, 0x20000
	global_load_lds_dwordx4 v172, s[10:11]
	s_mov_b32 m0, s45
	s_addc_u32 s5, s11, 0
	s_add_i32 s54, s44, 0x4000
	global_load_lds_dwordx4 v132, s[10:11]
	s_mov_b32 m0, s54
	s_add_i32 s55, s44, 0x6000
	global_load_lds_dwordx4 v172, s[4:5]
	s_mov_b32 m0, s55
	v_mov_b32_e32 v129, v173
	global_load_lds_dwordx4 v132, s[4:5]
	s_load_dwordx4 s[4:7], s[16:17], 0x80
	s_waitcnt vmcnt(0)
	v_mov_b32_e32 v131, v173
	v_mov_b32_e32 v133, v173
	s_cmp_eq_u32 s24, 1
	v_lshl_add_u64 v[6:7], s[8:9], 0, v[128:129]
	v_lshl_add_u64 v[4:5], s[8:9], 0, v[130:131]
	v_lshl_add_u64 v[0:1], s[10:11], 0, v[172:173]
	s_cselect_b64 s[12:13], -1, 0
	s_cmp_lg_u32 s24, 1
	v_lshl_add_u64 v[2:3], s[10:11], 0, v[132:133]
	s_cbranch_scc1 .LBB0_980
	s_barrier

.LBB0_981:
	v_ashrrev_i32_e32 v2, 31, v0
	v_lshrrev_b32_e32 v2, 26, v2
	v_add_u32_e32 v2, v0, v2
	v_ashrrev_i32_e32 v3, 6, v2
	v_bfe_i32 v2, v0, 27, 1
	v_lshlrev_b32_e32 v1, 4, v0
	v_lshrrev_b32_e32 v2, 22, v2
	v_add_u32_e32 v2, v1, v2
	v_and_b32_e32 v2, 0xfffffc00, v2
	v_sub_u32_e32 v2, v1, v2
	v_lshrrev_b32_e32 v4, 4, v2
	v_bitop3_b32 v4, v4, v2, 32 bitop3:0x6c
	v_ashrrev_i32_e32 v2, 31, v2
	v_lshrrev_b32_e32 v2, 26, v2
	v_lshlrev_b32_e32 v5, 3, v3
	v_add_u32_e32 v2, v4, v2
	v_and_b32_e32 v5, -16, v5
	v_ashrrev_i32_e32 v6, 6, v2
	v_lshlrev_b32_e32 v3, 5, v3
	v_add_u32_e32 v2, v6, v5
	v_and_b32_e32 v5, 32, v3
	v_mul_i32_i24_e32 v3, 64, v6
	v_sub_u32_e32 v3, v4, v3
	v_ashrrev_i16_sdwa v3, v196, sext(v3) dst_sel:DWORD dst_unused:UNUSED_PAD src0_sel:DWORD src1_sel:BYTE_0
	v_bfe_i32 v4, v3, 0, 16
	v_lshlrev_b32_e32 v3, 1, v2
	v_lshrrev_b32_e32 v7, 2, v2
	v_and_b32_e32 v6, 3, v6
	s_mov_b32 s0, 0x1fffe0
	v_and_b32_e32 v3, 24, v3
	v_and_b32_e32 v7, 4, v7
	v_and_or_b32 v6, v2, s0, v6
	v_or3_b32 v6, v6, v7, v3
	v_and_b32_e32 v250, 15, v2
	v_bfe_u32 v251, v2, 4, 2
	v_lshl_or_b32 v250, v250, 2, v251
	v_and_b32_e32 v2, 0xffffffc0, v2
	v_or_b32_e32 v2, v2, v250
	v_lshrrev_b32_e32 v3, 6, v2
	v_mad_u64_u32 v[2:3], s[4:5], v3, 62, v[2:3]
	v_add_lshl_u32 v3, v5, v4, 1
	v_add_u32_e32 v1, 0x2000, v1
	v_lshl_add_u32 v172, v2, 11, v3
	v_ashrrev_i32_e32 v2, 31, v1
	v_lshrrev_b32_e32 v2, 22, v2
	v_add_u32_e32 v2, v1, v2
	v_lshl_add_u32 v128, v6, 11, v3
	v_ashrrev_i32_e32 v3, 10, v2
	v_mul_i32_i24_e32 v2, 0x400, v3
	v_sub_u32_e32 v1, v1, v2
	v_lshrrev_b32_e32 v2, 4, v1
	v_bitop3_b32 v1, v2, v1, 32 bitop3:0x6c
	v_ashrrev_i32_e32 v4, 31, v1
	v_lshrrev_b32_e32 v4, 26, v4
	v_lshlrev_b32_e32 v2, 3, v3
	v_add_u32_e32 v4, v1, v4
	v_and_b32_e32 v2, -16, v2
	v_ashrrev_i32_e32 v5, 6, v4
	v_lshlrev_b32_e32 v3, 5, v3
	v_add_u32_e32 v2, v5, v2
	v_and_b32_e32 v6, 32, v3
	v_and_b32_e32 v3, 0xc0, v4
	v_sub_u32_e32 v1, v1, v3
	v_lshlrev_b32_e32 v3, 1, v2
	v_lshrrev_b32_e32 v4, 2, v2
	v_and_b32_e32 v5, 3, v5
	v_ashrrev_i16_sdwa v1, v196, sext(v1) dst_sel:DWORD dst_unused:UNUSED_PAD src0_sel:DWORD src1_sel:BYTE_0
	v_and_b32_e32 v3, 24, v3
	v_and_b32_e32 v4, 4, v4
	v_and_or_b32 v5, v2, s0, v5
	v_bfe_i32 v1, v1, 0, 16
	v_or3_b32 v4, v5, v4, v3
	v_and_b32_e32 v250, 15, v2
	v_bfe_u32 v251, v2, 4, 2
	v_lshl_or_b32 v250, v250, 2, v251
	v_and_b32_e32 v2, 0xffffffc0, v2
	v_or_b32_e32 v2, v2, v250
	v_lshrrev_b32_e32 v3, 6, v2
	v_mad_u64_u32 v[2:3], s[4:5], v3, 62, v[2:3]
	v_add_lshl_u32 v1, v6, v1, 1
	v_lshl_add_u32 v132, v2, 11, v1
	v_and_b32_e32 v2, 15, v0
	v_lshl_add_u32 v130, v4, 11, v1
	v_or_b32_e32 v1, s56, v2
	v_and_b32_e32 v3, 48, v0
	v_lshlrev_b32_e32 v4, 6, v1
	v_lshlrev_b32_e32 v1, 2, v1
	v_lshlrev_b32_e32 v0, 2, v0
	v_and_b32_e32 v4, 0x3c0, v4
	v_and_b32_e32 v1, 32, v1
	v_lshlrev_b32_e32 v2, 6, v2
	v_and_b32_e32 v0, 32, v0
	v_bitop3_b32 v1, v4, v1, v3 bitop3:0x36
	v_bitop3_b32 v0, v2, v0, v3 bitop3:0x36
	s_mov_b64 s[4:5], 0

.LBB0_993:
	v_mov_b32_e32 v134, v192
	v_mov_b32_e32 v135, v192
	s_lshl_b32 s6, s30, 7
	v_bfe_i32 v128, v135, 7, 1
	v_and_b32_e32 v128, 0xb00, v128
	v_add_u32_e32 v128, s6, v128
	s_movk_i32 s7, 0x7f
	v_and_or_b32 v128, v135, s7, v128
	v_ashrrev_i32_e32 v129, 31, v128
	v_lshl_add_u64 v[130:131], v[128:129], 2, s[20:21]
	v_ashrrev_i32_e32 v129, 8, v135
	v_mad_i32_i24 v132, v129, s79, v128
	v_ashrrev_i32_e32 v133, 31, v132
	v_lshl_add_u64 v[132:133], v[132:133], 2, s[18:19]
	v_cmp_gt_i32_e32 vcc, 3, v129
	v_add_u32_e32 v129, 0x200, v135
	v_lshl_add_u32 v135, v135, 2, 0
	v_cndmask_b32_e32 v133, v131, v133, vcc
	v_cndmask_b32_e32 v132, v130, v132, vcc
	global_load_dword v132, v[132:133], off
	v_ashrrev_i32_e32 v133, 8, v129
	v_mad_i32_i24 v128, v133, s79, v128
	v_ashrrev_i32_e32 v129, 31, v128
	v_lshl_add_u64 v[128:129], v[128:129], 2, s[18:19]
	v_cmp_gt_i32_e32 vcc, 3, v133
	s_mulk_i32 s0, 0xfc
	v_lshrrev_b32_e32 v136, 1, v134
	v_cndmask_b32_e32 v129, v131, v129, vcc
	v_cndmask_b32_e32 v128, v130, v128, vcc
	global_load_dword v133, v[128:129], off
	v_add_u32_e32 v135, 0x20000, v135
	s_add_i32 s0, s66, s0
	v_and_b32_e32 v219, 15, v134
	v_and_or_b32 v134, v136, 24, s62
	v_add_u32_e32 v218, s0, v219
	v_or_b32_e32 v136, 0x80, v134
	v_or_b32_e32 v137, 4, v134
	v_or_b32_e32 v138, 0x84, v134
	v_cmp_lt_u32_e32 vcc, 1, v219
	v_or_b32_e32 v188, s6, v134
	v_cmp_gt_i32_e64 s[6:7], s58, v218
	v_lshlrev_b32_e32 v172, 2, v134
	v_lshlrev_b32_e32 v210, 2, v137
	v_lshlrev_b32_e32 v206, 2, v136
	v_lshlrev_b32_e32 v212, 2, v138
	v_ashrrev_i32_e32 v189, 31, v188
	s_and_b64 s[6:7], vcc, s[6:7]
	s_waitcnt vmcnt(0)
	ds_write2st64_b32 v135, v132, v133 offset1:8
	s_waitcnt lgkmcnt(0)
	s_barrier
	v_add_u32_e32 v203, 0x20000, v172
	ds_read_b128 v[128:131], v203 offset:0
	ds_read_b128 v[132:135], v203 offset:512
	ds_read_b128 v[136:139], v203 offset:1024
	ds_read_b128 v[140:143], v203 offset:1536
	ds_read_b128 v[144:147], v203 offset:2048
	ds_read_b128 v[148:151], v203 offset:2560
	ds_read_b128 v[152:155], v203 offset:3072
	ds_read_b128 v[156:159], v203 offset:3584
	v_lshl_add_u64 v[190:191], v[188:189], 1, s[16:17]
	v_mad_u32_u24 v174, v219, 3, v218
	s_add_i32 s6, s0, 2191
	s_mul_hi_u32 s7, s6, s59
	s_lshr_b32 s7, s7, 7
	s_mulk_i32 s7, 0x810
	s_sub_i32 s6, s6, s7
	s_waitcnt lgkmcnt(0)
	s_cmp_lt_u32 s6, 127
	s_cbranch_scc1 .Lffn1e_slowall
	s_mov_b32 s6, 0x10001
	s_mov_b32 s7, 0x10001
	s_nop 0
	v_cndmask_b32_e64 v160, 0, v136, s[6:7]
	v_cndmask_b32_e64 v161, 0, v137, s[6:7]
	v_cndmask_b32_e64 v162, 0, v138, s[6:7]
	v_cndmask_b32_e64 v163, 0, v139, s[6:7]
	v_cndmask_b32_e64 v164, 0, v140, s[6:7]
	v_cndmask_b32_e64 v165, 0, v141, s[6:7]
	v_cndmask_b32_e64 v166, 0, v142, s[6:7]
	v_cndmask_b32_e64 v167, 0, v143, s[6:7]
	v_cndmask_b32_e64 v168, 0, v128, s[6:7]
	v_cndmask_b32_e64 v169, 0, v129, s[6:7]
	v_cndmask_b32_e64 v170, 0, v130, s[6:7]
	v_cndmask_b32_e64 v171, 0, v131, s[6:7]
	v_cndmask_b32_e64 v204, 0, v132, s[6:7]
	v_cndmask_b32_e64 v205, 0, v133, s[6:7]
	v_cndmask_b32_e64 v206, 0, v134, s[6:7]
	v_cndmask_b32_e64 v207, 0, v135, s[6:7]
	v_fma_f32 v236, v124, v144, v152
	v_fma_f32 v237, v125, v145, v153
	v_fma_f32 v238, v126, v146, v154
	v_fma_f32 v239, v127, v147, v155
	v_fmac_f32_dpp v236, v76, v136 row_shr:1 row_mask:0xf bank_mask:0xf bound_ctrl:1
	v_fmac_f32_dpp v237, v77, v137 row_shr:1 row_mask:0xf bank_mask:0xf bound_ctrl:1
	v_fmac_f32_dpp v238, v78, v138 row_shr:1 row_mask:0xf bank_mask:0xf bound_ctrl:1
	v_fmac_f32_dpp v239, v79, v139 row_shr:1 row_mask:0xf bank_mask:0xf bound_ctrl:1
	v_fmac_f32_dpp v236, v92, v128 row_shr:1 row_mask:0xf bank_mask:0xf bound_ctrl:1
	v_fmac_f32_dpp v237, v93, v129 row_shr:1 row_mask:0xf bank_mask:0xf bound_ctrl:1
	v_fmac_f32_dpp v238, v94, v130 row_shr:1 row_mask:0xf bank_mask:0xf bound_ctrl:1
	v_fmac_f32_dpp v239, v95, v131 row_shr:1 row_mask:0xf bank_mask:0xf bound_ctrl:1
	v_fma_f32 v240, v116, v148, v156
	v_fma_f32 v241, v117, v149, v157
	v_fma_f32 v242, v118, v150, v158
	v_fma_f32 v243, v119, v151, v159
	v_fmac_f32_dpp v240, v68, v140 row_shr:1 row_mask:0xf bank_mask:0xf bound_ctrl:1
	v_fmac_f32_dpp v241, v69, v141 row_shr:1 row_mask:0xf bank_mask:0xf bound_ctrl:1
	v_fmac_f32_dpp v242, v70, v142 row_shr:1 row_mask:0xf bank_mask:0xf bound_ctrl:1
	v_fmac_f32_dpp v243, v71, v143 row_shr:1 row_mask:0xf bank_mask:0xf bound_ctrl:1
	v_fmac_f32_dpp v240, v84, v132 row_shr:1 row_mask:0xf bank_mask:0xf bound_ctrl:1
	v_fmac_f32_dpp v241, v85, v133 row_shr:1 row_mask:0xf bank_mask:0xf bound_ctrl:1
	v_fmac_f32_dpp v242, v86, v134 row_shr:1 row_mask:0xf bank_mask:0xf bound_ctrl:1
	v_fmac_f32_dpp v243, v87, v135 row_shr:1 row_mask:0xf bank_mask:0xf bound_ctrl:1
	v_mov_b32_e32 v228, 0xbdd2d3e8
	v_mul_f32_e32 v244, v236, v236
	v_mul_f32_e32 v245, v237, v237
	v_mul_f32_e32 v246, v238, v238
	v_mul_f32_e32 v247, v239, v239
	v_fmaak_f32 v244, v244, v228, 0xc0135761
	v_fmaak_f32 v245, v245, v228, 0xc0135761
	v_fmaak_f32 v246, v246, v228, 0xc0135761
	v_fmaak_f32 v247, v247, v228, 0xc0135761
	v_mul_f32_e32 v244, v236, v244
	v_mul_f32_e32 v245, v237, v245
	v_mul_f32_e32 v246, v238, v246
	v_mul_f32_e32 v247, v239, v247
	v_exp_f32_e32 v244, v244
	v_exp_f32_e32 v245, v245
	v_exp_f32_e32 v246, v246
	v_exp_f32_e32 v247, v247
	v_add_f32_e32 v244, 1.0, v244
	v_add_f32_e32 v245, 1.0, v245
	v_add_f32_e32 v246, 1.0, v246
	v_add_f32_e32 v247, 1.0, v247
	v_rcp_f32_e32 v244, v244
	v_rcp_f32_e32 v245, v245
	v_rcp_f32_e32 v246, v246
	v_rcp_f32_e32 v247, v247
	v_mul_f32_e32 v244, v236, v244
	v_mul_f32_e32 v245, v237, v245
	v_mul_f32_e32 v246, v238, v246
	v_mul_f32_e32 v247, v239, v247
	v_mul_f32_e32 v248, v240, v244
	v_mul_f32_e32 v249, v241, v245
	v_mul_f32_e32 v250, v242, v246
	v_mul_f32_e32 v251, v243, v247
	v_cvt_pk_bf16_f32 v208, v248, v249
	v_cvt_pk_bf16_f32 v209, v250, v251
	v_fma_f32 v236, v108, v144, v152
	v_fma_f32 v237, v109, v145, v153
	v_fma_f32 v238, v110, v146, v154
	v_fma_f32 v239, v111, v147, v155
	v_fmac_f32_e32 v236, v124, v136
	v_fmac_f32_e32 v237, v125, v137
	v_fmac_f32_e32 v238, v126, v138
	v_fmac_f32_e32 v239, v127, v139
	v_fmac_f32_dpp v236, v76, v128 row_shr:1 row_mask:0xf bank_mask:0xf bound_ctrl:1
	v_fmac_f32_dpp v237, v77, v129 row_shr:1 row_mask:0xf bank_mask:0xf bound_ctrl:1
	v_fmac_f32_dpp v238, v78, v130 row_shr:1 row_mask:0xf bank_mask:0xf bound_ctrl:1
	v_fmac_f32_dpp v239, v79, v131 row_shr:1 row_mask:0xf bank_mask:0xf bound_ctrl:1
	v_fma_f32 v240, v100, v148, v156
	v_fma_f32 v241, v101, v149, v157
	v_fma_f32 v242, v102, v150, v158
	v_fma_f32 v243, v103, v151, v159
	v_fmac_f32_e32 v240, v116, v140
	v_fmac_f32_e32 v241, v117, v141
	v_fmac_f32_e32 v242, v118, v142
	v_fmac_f32_e32 v243, v119, v143
	v_fmac_f32_dpp v240, v68, v132 row_shr:1 row_mask:0xf bank_mask:0xf bound_ctrl:1
	v_fmac_f32_dpp v241, v69, v133 row_shr:1 row_mask:0xf bank_mask:0xf bound_ctrl:1
	v_fmac_f32_dpp v242, v70, v134 row_shr:1 row_mask:0xf bank_mask:0xf bound_ctrl:1
	v_fmac_f32_dpp v243, v71, v135 row_shr:1 row_mask:0xf bank_mask:0xf bound_ctrl:1
	v_mov_b32_e32 v228, 0xbdd2d3e8
	v_mul_f32_e32 v244, v236, v236
	v_mul_f32_e32 v245, v237, v237
	v_mul_f32_e32 v246, v238, v238
	v_mul_f32_e32 v247, v239, v239
	v_fmaak_f32 v244, v244, v228, 0xc0135761
	v_fmaak_f32 v245, v245, v228, 0xc0135761
	v_fmaak_f32 v246, v246, v228, 0xc0135761
	v_fmaak_f32 v247, v247, v228, 0xc0135761
	v_mul_f32_e32 v244, v236, v244
	v_mul_f32_e32 v245, v237, v245
	v_mul_f32_e32 v246, v238, v246
	v_mul_f32_e32 v247, v239, v247
	v_exp_f32_e32 v244, v244
	v_exp_f32_e32 v245, v245
	v_exp_f32_e32 v246, v246
	v_exp_f32_e32 v247, v247
	v_add_f32_e32 v244, 1.0, v244
	v_add_f32_e32 v245, 1.0, v245
	v_add_f32_e32 v246, 1.0, v246
	v_add_f32_e32 v247, 1.0, v247
	v_rcp_f32_e32 v244, v244
	v_rcp_f32_e32 v245, v245
	v_rcp_f32_e32 v246, v246
	v_rcp_f32_e32 v247, v247
	v_mul_f32_e32 v244, v236, v244
	v_mul_f32_e32 v245, v237, v245
	v_mul_f32_e32 v246, v238, v246
	v_mul_f32_e32 v247, v239, v247
	v_mul_f32_e32 v248, v240, v244
	v_mul_f32_e32 v249, v241, v245
	v_mul_f32_e32 v250, v242, v246
	v_mul_f32_e32 v251, v243, v247
	v_cvt_pk_bf16_f32 v210, v248, v249
	v_cvt_pk_bf16_f32 v211, v250, v251
	v_fma_f32 v236, v92, v144, v152
	v_fma_f32 v237, v93, v145, v153
	v_fma_f32 v238, v94, v146, v154
	v_fma_f32 v239, v95, v147, v155
	v_fmac_f32_e32 v236, v108, v136
	v_fmac_f32_e32 v237, v109, v137
	v_fmac_f32_e32 v238, v110, v138
	v_fmac_f32_e32 v239, v111, v139
	v_fmac_f32_e32 v236, v124, v128
	v_fmac_f32_e32 v237, v125, v129
	v_fmac_f32_e32 v238, v126, v130
	v_fmac_f32_e32 v239, v127, v131
	v_fma_f32 v240, v84, v148, v156
	v_fma_f32 v241, v85, v149, v157
	v_fma_f32 v242, v86, v150, v158
	v_fma_f32 v243, v87, v151, v159
	v_fmac_f32_e32 v240, v100, v140
	v_fmac_f32_e32 v241, v101, v141
	v_fmac_f32_e32 v242, v102, v142
	v_fmac_f32_e32 v243, v103, v143
	v_fmac_f32_e32 v240, v116, v132
	v_fmac_f32_e32 v241, v117, v133
	v_fmac_f32_e32 v242, v118, v134
	v_fmac_f32_e32 v243, v119, v135
	v_mov_b32_e32 v228, 0xbdd2d3e8
	v_mul_f32_e32 v244, v236, v236
	v_mul_f32_e32 v245, v237, v237
	v_mul_f32_e32 v246, v238, v238
	v_mul_f32_e32 v247, v239, v239
	v_fmaak_f32 v244, v244, v228, 0xc0135761
	v_fmaak_f32 v245, v245, v228, 0xc0135761
	v_fmaak_f32 v246, v246, v228, 0xc0135761
	v_fmaak_f32 v247, v247, v228, 0xc0135761
	v_mul_f32_e32 v244, v236, v244
	v_mul_f32_e32 v245, v237, v245
	v_mul_f32_e32 v246, v238, v246
	v_mul_f32_e32 v247, v239, v247
	v_exp_f32_e32 v244, v244
	v_exp_f32_e32 v245, v245
	v_exp_f32_e32 v246, v246
	v_exp_f32_e32 v247, v247
	v_add_f32_e32 v244, 1.0, v244
	v_add_f32_e32 v245, 1.0, v245
	v_add_f32_e32 v246, 1.0, v246
	v_add_f32_e32 v247, 1.0, v247
	v_rcp_f32_e32 v244, v244
	v_rcp_f32_e32 v245, v245
	v_rcp_f32_e32 v246, v246
	v_rcp_f32_e32 v247, v247
	v_mul_f32_e32 v244, v236, v244
	v_mul_f32_e32 v245, v237, v245
	v_mul_f32_e32 v246, v238, v246
	v_mul_f32_e32 v247, v239, v247
	v_mul_f32_e32 v248, v240, v244
	v_mul_f32_e32 v249, v241, v245
	v_mul_f32_e32 v250, v242, v246
	v_mul_f32_e32 v251, v243, v247
	v_cvt_pk_bf16_f32 v212, v248, v249
	v_cvt_pk_bf16_f32 v213, v250, v251
	v_fma_f32 v236, v76, v144, v152
	v_fma_f32 v237, v77, v145, v153
	v_fma_f32 v238, v78, v146, v154
	v_fma_f32 v239, v79, v147, v155
	v_fmac_f32_e32 v236, v92, v136
	v_fmac_f32_e32 v237, v93, v137
	v_fmac_f32_e32 v238, v94, v138
	v_fmac_f32_e32 v239, v95, v139
	v_fmac_f32_e32 v236, v108, v128
	v_fmac_f32_e32 v237, v109, v129
	v_fmac_f32_e32 v238, v110, v130
	v_fmac_f32_e32 v239, v111, v131
	v_fma_f32 v240, v68, v148, v156
	v_fma_f32 v241, v69, v149, v157
	v_fma_f32 v242, v70, v150, v158
	v_fma_f32 v243, v71, v151, v159
	v_fmac_f32_e32 v240, v84, v140
	v_fmac_f32_e32 v241, v85, v141
	v_fmac_f32_e32 v242, v86, v142
	v_fmac_f32_e32 v243, v87, v143
	v_fmac_f32_e32 v240, v100, v132
	v_fmac_f32_e32 v241, v101, v133
	v_fmac_f32_e32 v242, v102, v134
	v_fmac_f32_e32 v243, v103, v135
	v_mov_b32_e32 v228, 0xbdd2d3e8
	v_mul_f32_e32 v244, v236, v236
	v_mul_f32_e32 v245, v237, v237
	v_mul_f32_e32 v246, v238, v238
	v_mul_f32_e32 v247, v239, v239
	v_fmaak_f32 v244, v244, v228, 0xc0135761
	v_fmaak_f32 v245, v245, v228, 0xc0135761
	v_fmaak_f32 v246, v246, v228, 0xc0135761
	v_fmaak_f32 v247, v247, v228, 0xc0135761
	v_mul_f32_e32 v244, v236, v244
	v_mul_f32_e32 v245, v237, v245
	v_mul_f32_e32 v246, v238, v246
	v_mul_f32_e32 v247, v239, v247
	v_exp_f32_e32 v244, v244
	v_exp_f32_e32 v245, v245
	v_exp_f32_e32 v246, v246
	v_exp_f32_e32 v247, v247
	v_add_f32_e32 v244, 1.0, v244
	v_add_f32_e32 v245, 1.0, v245
	v_add_f32_e32 v246, 1.0, v246
	v_add_f32_e32 v247, 1.0, v247
	v_rcp_f32_e32 v244, v244
	v_rcp_f32_e32 v245, v245
	v_rcp_f32_e32 v246, v246
	v_rcp_f32_e32 v247, v247
	v_mul_f32_e32 v244, v236, v244
	v_mul_f32_e32 v245, v237, v245
	v_mul_f32_e32 v246, v238, v246
	v_mul_f32_e32 v247, v239, v247
	v_mul_f32_e32 v248, v240, v244
	v_mul_f32_e32 v249, v241, v245
	v_mul_f32_e32 v250, v242, v246
	v_mul_f32_e32 v251, v243, v247
	v_cvt_pk_bf16_f32 v214, v248, v249
	v_cvt_pk_bf16_f32 v215, v250, v251
	v_fma_f32 v236, v60, v144, v152
	v_fma_f32 v237, v61, v145, v153
	v_fma_f32 v238, v62, v146, v154
	v_fma_f32 v239, v63, v147, v155
	v_fmac_f32_dpp v236, v4, v136 row_shr:1 row_mask:0xf bank_mask:0xf bound_ctrl:1
	v_fmac_f32_dpp v237, v5, v137 row_shr:1 row_mask:0xf bank_mask:0xf bound_ctrl:1
	v_fmac_f32_dpp v238, v6, v138 row_shr:1 row_mask:0xf bank_mask:0xf bound_ctrl:1
	v_fmac_f32_dpp v239, v7, v139 row_shr:1 row_mask:0xf bank_mask:0xf bound_ctrl:1
	v_fmac_f32_dpp v236, v76, v160 row_ror:1 row_mask:0xf bank_mask:0xf
	v_fmac_f32_dpp v237, v77, v161 row_ror:1 row_mask:0xf bank_mask:0xf
	v_fmac_f32_dpp v238, v78, v162 row_ror:1 row_mask:0xf bank_mask:0xf
	v_fmac_f32_dpp v239, v79, v163 row_ror:1 row_mask:0xf bank_mask:0xf
	v_fmac_f32_dpp v236, v28, v128 row_shr:1 row_mask:0xf bank_mask:0xf bound_ctrl:1
	v_fmac_f32_dpp v237, v29, v129 row_shr:1 row_mask:0xf bank_mask:0xf bound_ctrl:1
	v_fmac_f32_dpp v238, v30, v130 row_shr:1 row_mask:0xf bank_mask:0xf bound_ctrl:1
	v_fmac_f32_dpp v239, v31, v131 row_shr:1 row_mask:0xf bank_mask:0xf bound_ctrl:1
	v_fmac_f32_dpp v236, v92, v168 row_ror:1 row_mask:0xf bank_mask:0xf
	v_fmac_f32_dpp v237, v93, v169 row_ror:1 row_mask:0xf bank_mask:0xf
	v_fmac_f32_dpp v238, v94, v170 row_ror:1 row_mask:0xf bank_mask:0xf
	v_fmac_f32_dpp v239, v95, v171 row_ror:1 row_mask:0xf bank_mask:0xf
	v_fma_f32 v240, v52, v148, v156
	v_fma_f32 v241, v53, v149, v157
	v_fma_f32 v242, v54, v150, v158
	v_fma_f32 v243, v55, v151, v159
	v_fmac_f32_dpp v240, v8, v140 row_shr:1 row_mask:0xf bank_mask:0xf bound_ctrl:1
	v_fmac_f32_dpp v241, v9, v141 row_shr:1 row_mask:0xf bank_mask:0xf bound_ctrl:1
	v_fmac_f32_dpp v242, v10, v142 row_shr:1 row_mask:0xf bank_mask:0xf bound_ctrl:1
	v_fmac_f32_dpp v243, v11, v143 row_shr:1 row_mask:0xf bank_mask:0xf bound_ctrl:1
	v_fmac_f32_dpp v240, v68, v164 row_ror:1 row_mask:0xf bank_mask:0xf
	v_fmac_f32_dpp v241, v69, v165 row_ror:1 row_mask:0xf bank_mask:0xf
	v_fmac_f32_dpp v242, v70, v166 row_ror:1 row_mask:0xf bank_mask:0xf
	v_fmac_f32_dpp v243, v71, v167 row_ror:1 row_mask:0xf bank_mask:0xf
	v_fmac_f32_dpp v240, v20, v132 row_shr:1 row_mask:0xf bank_mask:0xf bound_ctrl:1
	v_fmac_f32_dpp v241, v21, v133 row_shr:1 row_mask:0xf bank_mask:0xf bound_ctrl:1
	v_fmac_f32_dpp v242, v22, v134 row_shr:1 row_mask:0xf bank_mask:0xf bound_ctrl:1
	v_fmac_f32_dpp v243, v23, v135 row_shr:1 row_mask:0xf bank_mask:0xf bound_ctrl:1
	v_fmac_f32_dpp v240, v84, v204 row_ror:1 row_mask:0xf bank_mask:0xf
	v_fmac_f32_dpp v241, v85, v205 row_ror:1 row_mask:0xf bank_mask:0xf
	v_fmac_f32_dpp v242, v86, v206 row_ror:1 row_mask:0xf bank_mask:0xf
	v_fmac_f32_dpp v243, v87, v207 row_ror:1 row_mask:0xf bank_mask:0xf
	v_mov_b32_e32 v228, 0xbdd2d3e8
	v_mul_f32_e32 v244, v236, v236
	v_mul_f32_e32 v245, v237, v237
	v_mul_f32_e32 v246, v238, v238
	v_mul_f32_e32 v247, v239, v239
	v_fmaak_f32 v244, v244, v228, 0xc0135761
	v_fmaak_f32 v245, v245, v228, 0xc0135761
	v_fmaak_f32 v246, v246, v228, 0xc0135761
	v_fmaak_f32 v247, v247, v228, 0xc0135761
	v_mul_f32_e32 v244, v236, v244
	v_mul_f32_e32 v245, v237, v245
	v_mul_f32_e32 v246, v238, v246
	v_mul_f32_e32 v247, v239, v247
	v_exp_f32_e32 v244, v244
	v_exp_f32_e32 v245, v245
	v_exp_f32_e32 v246, v246
	v_exp_f32_e32 v247, v247
	v_add_f32_e32 v244, 1.0, v244
	v_add_f32_e32 v245, 1.0, v245
	v_add_f32_e32 v246, 1.0, v246
	v_add_f32_e32 v247, 1.0, v247
	v_rcp_f32_e32 v244, v244
	v_rcp_f32_e32 v245, v245
	v_rcp_f32_e32 v246, v246
	v_rcp_f32_e32 v247, v247
	v_mul_f32_e32 v244, v236, v244
	v_mul_f32_e32 v245, v237, v245
	v_mul_f32_e32 v246, v238, v246
	v_mul_f32_e32 v247, v239, v247
	v_mul_f32_e32 v248, v240, v244
	v_mul_f32_e32 v249, v241, v245
	v_mul_f32_e32 v250, v242, v246
	v_mul_f32_e32 v251, v243, v247
	v_cvt_pk_bf16_f32 v216, v248, v249
	v_cvt_pk_bf16_f32 v217, v250, v251
	v_fma_f32 v236, v44, v144, v152
	v_fma_f32 v237, v45, v145, v153
	v_fma_f32 v238, v46, v146, v154
	v_fma_f32 v239, v47, v147, v155
	v_fmac_f32_e32 v236, v60, v136
	v_fmac_f32_e32 v237, v61, v137
	v_fmac_f32_e32 v238, v62, v138
	v_fmac_f32_e32 v239, v63, v139
	v_fmac_f32_dpp v236, v4, v128 row_shr:1 row_mask:0xf bank_mask:0xf bound_ctrl:1
	v_fmac_f32_dpp v237, v5, v129 row_shr:1 row_mask:0xf bank_mask:0xf bound_ctrl:1
	v_fmac_f32_dpp v238, v6, v130 row_shr:1 row_mask:0xf bank_mask:0xf bound_ctrl:1
	v_fmac_f32_dpp v239, v7, v131 row_shr:1 row_mask:0xf bank_mask:0xf bound_ctrl:1
	v_fmac_f32_dpp v236, v76, v168 row_ror:1 row_mask:0xf bank_mask:0xf
	v_fmac_f32_dpp v237, v77, v169 row_ror:1 row_mask:0xf bank_mask:0xf
	v_fmac_f32_dpp v238, v78, v170 row_ror:1 row_mask:0xf bank_mask:0xf
	v_fmac_f32_dpp v239, v79, v171 row_ror:1 row_mask:0xf bank_mask:0xf
	v_fma_f32 v240, v36, v148, v156
	v_fma_f32 v241, v37, v149, v157
	v_fma_f32 v242, v38, v150, v158
	v_fma_f32 v243, v39, v151, v159
	v_fmac_f32_e32 v240, v52, v140
	v_fmac_f32_e32 v241, v53, v141
	v_fmac_f32_e32 v242, v54, v142
	v_fmac_f32_e32 v243, v55, v143
	v_fmac_f32_dpp v240, v8, v132 row_shr:1 row_mask:0xf bank_mask:0xf bound_ctrl:1
	v_fmac_f32_dpp v241, v9, v133 row_shr:1 row_mask:0xf bank_mask:0xf bound_ctrl:1
	v_fmac_f32_dpp v242, v10, v134 row_shr:1 row_mask:0xf bank_mask:0xf bound_ctrl:1
	v_fmac_f32_dpp v243, v11, v135 row_shr:1 row_mask:0xf bank_mask:0xf bound_ctrl:1
	v_fmac_f32_dpp v240, v68, v204 row_ror:1 row_mask:0xf bank_mask:0xf
	v_fmac_f32_dpp v241, v69, v205 row_ror:1 row_mask:0xf bank_mask:0xf
	v_fmac_f32_dpp v242, v70, v206 row_ror:1 row_mask:0xf bank_mask:0xf
	v_fmac_f32_dpp v243, v71, v207 row_ror:1 row_mask:0xf bank_mask:0xf
	v_mov_b32_e32 v228, 0xbdd2d3e8
	v_mul_f32_e32 v244, v236, v236
	v_mul_f32_e32 v245, v237, v237
	v_mul_f32_e32 v246, v238, v238
	v_mul_f32_e32 v247, v239, v239
	v_fmaak_f32 v244, v244, v228, 0xc0135761
	v_fmaak_f32 v245, v245, v228, 0xc0135761
	v_fmaak_f32 v246, v246, v228, 0xc0135761
	v_fmaak_f32 v247, v247, v228, 0xc0135761
	v_mul_f32_e32 v244, v236, v244
	v_mul_f32_e32 v245, v237, v245
	v_mul_f32_e32 v246, v238, v246
	v_mul_f32_e32 v247, v239, v247
	v_exp_f32_e32 v244, v244
	v_exp_f32_e32 v245, v245
	v_exp_f32_e32 v246, v246
	v_exp_f32_e32 v247, v247
	v_add_f32_e32 v244, 1.0, v244
	v_add_f32_e32 v245, 1.0, v245
	v_add_f32_e32 v246, 1.0, v246
	v_add_f32_e32 v247, 1.0, v247
	v_rcp_f32_e32 v244, v244
	v_rcp_f32_e32 v245, v245
	v_rcp_f32_e32 v246, v246
	v_rcp_f32_e32 v247, v247
	v_mul_f32_e32 v244, v236, v244
	v_mul_f32_e32 v245, v237, v245
	v_mul_f32_e32 v246, v238, v246
	v_mul_f32_e32 v247, v239, v247
	v_mul_f32_e32 v248, v240, v244
	v_mul_f32_e32 v249, v241, v245
	v_mul_f32_e32 v250, v242, v246
	v_mul_f32_e32 v251, v243, v247
	v_cvt_pk_bf16_f32 v220, v248, v249
	v_cvt_pk_bf16_f32 v221, v250, v251
	v_fma_f32 v236, v28, v144, v152
	v_fma_f32 v237, v29, v145, v153
	v_fma_f32 v238, v30, v146, v154
	v_fma_f32 v239, v31, v147, v155
	v_fmac_f32_e32 v236, v44, v136
	v_fmac_f32_e32 v237, v45, v137
	v_fmac_f32_e32 v238, v46, v138
	v_fmac_f32_e32 v239, v47, v139
	v_fmac_f32_e32 v236, v60, v128
	v_fmac_f32_e32 v237, v61, v129
	v_fmac_f32_e32 v238, v62, v130
	v_fmac_f32_e32 v239, v63, v131
	v_fma_f32 v240, v20, v148, v156
	v_fma_f32 v241, v21, v149, v157
	v_fma_f32 v242, v22, v150, v158
	v_fma_f32 v243, v23, v151, v159
	v_fmac_f32_e32 v240, v36, v140
	v_fmac_f32_e32 v241, v37, v141
	v_fmac_f32_e32 v242, v38, v142
	v_fmac_f32_e32 v243, v39, v143
	v_fmac_f32_e32 v240, v52, v132
	v_fmac_f32_e32 v241, v53, v133
	v_fmac_f32_e32 v242, v54, v134
	v_fmac_f32_e32 v243, v55, v135
	v_mov_b32_e32 v228, 0xbdd2d3e8
	v_mul_f32_e32 v244, v236, v236
	v_mul_f32_e32 v245, v237, v237
	v_mul_f32_e32 v246, v238, v238
	v_mul_f32_e32 v247, v239, v239
	v_fmaak_f32 v244, v244, v228, 0xc0135761
	v_fmaak_f32 v245, v245, v228, 0xc0135761
	v_fmaak_f32 v246, v246, v228, 0xc0135761
	v_fmaak_f32 v247, v247, v228, 0xc0135761
	v_mul_f32_e32 v244, v236, v244
	v_mul_f32_e32 v245, v237, v245
	v_mul_f32_e32 v246, v238, v246
	v_mul_f32_e32 v247, v239, v247
	v_exp_f32_e32 v244, v244
	v_exp_f32_e32 v245, v245
	v_exp_f32_e32 v246, v246
	v_exp_f32_e32 v247, v247
	v_add_f32_e32 v244, 1.0, v244
	v_add_f32_e32 v245, 1.0, v245
	v_add_f32_e32 v246, 1.0, v246
	v_add_f32_e32 v247, 1.0, v247
	v_rcp_f32_e32 v244, v244
	v_rcp_f32_e32 v245, v245
	v_rcp_f32_e32 v246, v246
	v_rcp_f32_e32 v247, v247
	v_mul_f32_e32 v244, v236, v244
	v_mul_f32_e32 v245, v237, v245
	v_mul_f32_e32 v246, v238, v246
	v_mul_f32_e32 v247, v239, v247
	v_mul_f32_e32 v248, v240, v244
	v_mul_f32_e32 v249, v241, v245
	v_mul_f32_e32 v250, v242, v246
	v_mul_f32_e32 v251, v243, v247
	v_cvt_pk_bf16_f32 v222, v248, v249
	v_cvt_pk_bf16_f32 v223, v250, v251
	v_fma_f32 v236, v4, v144, v152
	v_fma_f32 v237, v5, v145, v153
	v_fma_f32 v238, v6, v146, v154
	v_fma_f32 v239, v7, v147, v155
	v_fmac_f32_e32 v236, v28, v136
	v_fmac_f32_e32 v237, v29, v137
	v_fmac_f32_e32 v238, v30, v138
	v_fmac_f32_e32 v239, v31, v139
	v_fmac_f32_e32 v236, v44, v128
	v_fmac_f32_e32 v237, v45, v129
	v_fmac_f32_e32 v238, v46, v130
	v_fmac_f32_e32 v239, v47, v131
	v_fma_f32 v240, v8, v148, v156
	v_fma_f32 v241, v9, v149, v157
	v_fma_f32 v242, v10, v150, v158
	v_fma_f32 v243, v11, v151, v159
	v_fmac_f32_e32 v240, v20, v140
	v_fmac_f32_e32 v241, v21, v141
	v_fmac_f32_e32 v242, v22, v142
	v_fmac_f32_e32 v243, v23, v143
	v_fmac_f32_e32 v240, v36, v132
	v_fmac_f32_e32 v241, v37, v133
	v_fmac_f32_e32 v242, v38, v134
	v_fmac_f32_e32 v243, v39, v135
	v_mov_b32_e32 v228, 0xbdd2d3e8
	v_mul_f32_e32 v244, v236, v236
	v_mul_f32_e32 v245, v237, v237
	v_mul_f32_e32 v246, v238, v238
	v_mul_f32_e32 v247, v239, v239
	v_fmaak_f32 v244, v244, v228, 0xc0135761
	v_fmaak_f32 v245, v245, v228, 0xc0135761
	v_fmaak_f32 v246, v246, v228, 0xc0135761
	v_fmaak_f32 v247, v247, v228, 0xc0135761
	v_mul_f32_e32 v244, v236, v244
	v_mul_f32_e32 v245, v237, v245
	v_mul_f32_e32 v246, v238, v246
	v_mul_f32_e32 v247, v239, v247
	v_exp_f32_e32 v244, v244
	v_exp_f32_e32 v245, v245
	v_exp_f32_e32 v246, v246
	v_exp_f32_e32 v247, v247
	v_add_f32_e32 v244, 1.0, v244
	v_add_f32_e32 v245, 1.0, v245
	v_add_f32_e32 v246, 1.0, v246
	v_add_f32_e32 v247, 1.0, v247
	v_rcp_f32_e32 v244, v244
	v_rcp_f32_e32 v245, v245
	v_rcp_f32_e32 v246, v246
	v_rcp_f32_e32 v247, v247
	v_mul_f32_e32 v244, v236, v244
	v_mul_f32_e32 v245, v237, v245
	v_mul_f32_e32 v246, v238, v246
	v_mul_f32_e32 v247, v239, v247
	v_mul_f32_e32 v248, v240, v244
	v_mul_f32_e32 v249, v241, v245
	v_mul_f32_e32 v250, v242, v246
	v_mul_f32_e32 v251, v243, v247
	v_cvt_pk_bf16_f32 v224, v248, v249
	v_cvt_pk_bf16_f32 v225, v250, v251
	ds_read_b128 v[128:131], v203 offset:16
	ds_read_b128 v[132:135], v203 offset:528
	ds_read_b128 v[136:139], v203 offset:1040
	ds_read_b128 v[140:143], v203 offset:1552
	ds_read_b128 v[144:147], v203 offset:2064
	ds_read_b128 v[148:151], v203 offset:2576
	ds_read_b128 v[152:155], v203 offset:3088
	ds_read_b128 v[156:159], v203 offset:3600
	s_waitcnt lgkmcnt(0)
	s_mov_b32 s6, 0x10001
	s_mov_b32 s7, 0x10001
	s_nop 0
	v_cndmask_b32_e64 v160, 0, v136, s[6:7]
	v_cndmask_b32_e64 v161, 0, v137, s[6:7]
	v_cndmask_b32_e64 v162, 0, v138, s[6:7]
	v_cndmask_b32_e64 v163, 0, v139, s[6:7]
	v_cndmask_b32_e64 v164, 0, v140, s[6:7]
	v_cndmask_b32_e64 v165, 0, v141, s[6:7]
	v_cndmask_b32_e64 v166, 0, v142, s[6:7]
	v_cndmask_b32_e64 v167, 0, v143, s[6:7]
	v_cndmask_b32_e64 v168, 0, v128, s[6:7]
	v_cndmask_b32_e64 v169, 0, v129, s[6:7]
	v_cndmask_b32_e64 v170, 0, v130, s[6:7]
	v_cndmask_b32_e64 v171, 0, v131, s[6:7]
	v_cndmask_b32_e64 v204, 0, v132, s[6:7]
	v_cndmask_b32_e64 v205, 0, v133, s[6:7]
	v_cndmask_b32_e64 v206, 0, v134, s[6:7]
	v_cndmask_b32_e64 v207, 0, v135, s[6:7]
	v_fma_f32 v236, v120, v144, v152
	v_fma_f32 v237, v121, v145, v153
	v_fma_f32 v238, v122, v146, v154
	v_fma_f32 v239, v123, v147, v155
	v_fmac_f32_dpp v236, v72, v136 row_shr:1 row_mask:0xf bank_mask:0xf bound_ctrl:1
	v_fmac_f32_dpp v237, v73, v137 row_shr:1 row_mask:0xf bank_mask:0xf bound_ctrl:1
	v_fmac_f32_dpp v238, v74, v138 row_shr:1 row_mask:0xf bank_mask:0xf bound_ctrl:1
	v_fmac_f32_dpp v239, v75, v139 row_shr:1 row_mask:0xf bank_mask:0xf bound_ctrl:1
	v_fmac_f32_dpp v236, v88, v128 row_shr:1 row_mask:0xf bank_mask:0xf bound_ctrl:1
	v_fmac_f32_dpp v237, v89, v129 row_shr:1 row_mask:0xf bank_mask:0xf bound_ctrl:1
	v_fmac_f32_dpp v238, v90, v130 row_shr:1 row_mask:0xf bank_mask:0xf bound_ctrl:1
	v_fmac_f32_dpp v239, v91, v131 row_shr:1 row_mask:0xf bank_mask:0xf bound_ctrl:1
	v_fma_f32 v240, v112, v148, v156
	v_fma_f32 v241, v113, v149, v157
	v_fma_f32 v242, v114, v150, v158
	v_fma_f32 v243, v115, v151, v159
	v_fmac_f32_dpp v240, v64, v140 row_shr:1 row_mask:0xf bank_mask:0xf bound_ctrl:1
	v_fmac_f32_dpp v241, v65, v141 row_shr:1 row_mask:0xf bank_mask:0xf bound_ctrl:1
	v_fmac_f32_dpp v242, v66, v142 row_shr:1 row_mask:0xf bank_mask:0xf bound_ctrl:1
	v_fmac_f32_dpp v243, v67, v143 row_shr:1 row_mask:0xf bank_mask:0xf bound_ctrl:1
	v_fmac_f32_dpp v240, v80, v132 row_shr:1 row_mask:0xf bank_mask:0xf bound_ctrl:1
	v_fmac_f32_dpp v241, v81, v133 row_shr:1 row_mask:0xf bank_mask:0xf bound_ctrl:1
	v_fmac_f32_dpp v242, v82, v134 row_shr:1 row_mask:0xf bank_mask:0xf bound_ctrl:1
	v_fmac_f32_dpp v243, v83, v135 row_shr:1 row_mask:0xf bank_mask:0xf bound_ctrl:1
	v_mov_b32_e32 v228, 0xbdd2d3e8
	v_mul_f32_e32 v244, v236, v236
	v_mul_f32_e32 v245, v237, v237
	v_mul_f32_e32 v246, v238, v238
	v_mul_f32_e32 v247, v239, v239
	v_fmaak_f32 v244, v244, v228, 0xc0135761
	v_fmaak_f32 v245, v245, v228, 0xc0135761
	v_fmaak_f32 v246, v246, v228, 0xc0135761
	v_fmaak_f32 v247, v247, v228, 0xc0135761
	v_mul_f32_e32 v244, v236, v244
	v_mul_f32_e32 v245, v237, v245
	v_mul_f32_e32 v246, v238, v246
	v_mul_f32_e32 v247, v239, v247
	v_exp_f32_e32 v244, v244
	v_exp_f32_e32 v245, v245
	v_exp_f32_e32 v246, v246
	v_exp_f32_e32 v247, v247
	v_add_f32_e32 v244, 1.0, v244
	v_add_f32_e32 v245, 1.0, v245
	v_add_f32_e32 v246, 1.0, v246
	v_add_f32_e32 v247, 1.0, v247
	v_rcp_f32_e32 v244, v244
	v_rcp_f32_e32 v245, v245
	v_rcp_f32_e32 v246, v246
	v_rcp_f32_e32 v247, v247
	v_mul_f32_e32 v244, v236, v244
	v_mul_f32_e32 v245, v237, v245
	v_mul_f32_e32 v246, v238, v246
	v_mul_f32_e32 v247, v239, v247
	v_mul_f32_e32 v248, v240, v244
	v_mul_f32_e32 v249, v241, v245
	v_mul_f32_e32 v250, v242, v246
	v_mul_f32_e32 v251, v243, v247
	v_mov_b32_e32 v180, v208
	v_mov_b32_e32 v181, v209
	v_cvt_pk_bf16_f32 v182, v248, v249
	v_cvt_pk_bf16_f32 v183, v250, v251
	v_add_u32_e32 v252, 0, v174
	v_mad_i64_i32 v[226:227], vcc, v252, s79, v[190:191]
	v_cmp_lt_u32_e64 s[8:9], 0, v219
	v_cmp_gt_i32_e32 vcc, s58, v252
	s_nop 1
	s_and_b64 vcc, vcc, s[8:9]
	s_and_saveexec_b64 s[10:11], vcc
	global_store_dwordx4 v[226:227], v[180:183], off sc1
	s_mov_b64 exec, s[10:11]
	v_fma_f32 v236, v104, v144, v152
	v_fma_f32 v237, v105, v145, v153
	v_fma_f32 v238, v106, v146, v154
	v_fma_f32 v239, v107, v147, v155
	v_fmac_f32_e32 v236, v120, v136
	v_fmac_f32_e32 v237, v121, v137
	v_fmac_f32_e32 v238, v122, v138
	v_fmac_f32_e32 v239, v123, v139
	v_fmac_f32_dpp v236, v72, v128 row_shr:1 row_mask:0xf bank_mask:0xf bound_ctrl:1
	v_fmac_f32_dpp v237, v73, v129 row_shr:1 row_mask:0xf bank_mask:0xf bound_ctrl:1
	v_fmac_f32_dpp v238, v74, v130 row_shr:1 row_mask:0xf bank_mask:0xf bound_ctrl:1
	v_fmac_f32_dpp v239, v75, v131 row_shr:1 row_mask:0xf bank_mask:0xf bound_ctrl:1
	v_fma_f32 v240, v96, v148, v156
	v_fma_f32 v241, v97, v149, v157
	v_fma_f32 v242, v98, v150, v158
	v_fma_f32 v243, v99, v151, v159
	v_fmac_f32_e32 v240, v112, v140
	v_fmac_f32_e32 v241, v113, v141
	v_fmac_f32_e32 v242, v114, v142
	v_fmac_f32_e32 v243, v115, v143
	v_fmac_f32_dpp v240, v64, v132 row_shr:1 row_mask:0xf bank_mask:0xf bound_ctrl:1
	v_fmac_f32_dpp v241, v65, v133 row_shr:1 row_mask:0xf bank_mask:0xf bound_ctrl:1
	v_fmac_f32_dpp v242, v66, v134 row_shr:1 row_mask:0xf bank_mask:0xf bound_ctrl:1
	v_fmac_f32_dpp v243, v67, v135 row_shr:1 row_mask:0xf bank_mask:0xf bound_ctrl:1
	v_mov_b32_e32 v228, 0xbdd2d3e8
	v_mul_f32_e32 v244, v236, v236
	v_mul_f32_e32 v245, v237, v237
	v_mul_f32_e32 v246, v238, v238
	v_mul_f32_e32 v247, v239, v239
	v_fmaak_f32 v244, v244, v228, 0xc0135761
	v_fmaak_f32 v245, v245, v228, 0xc0135761
	v_fmaak_f32 v246, v246, v228, 0xc0135761
	v_fmaak_f32 v247, v247, v228, 0xc0135761
	v_mul_f32_e32 v244, v236, v244
	v_mul_f32_e32 v245, v237, v245
	v_mul_f32_e32 v246, v238, v246
	v_mul_f32_e32 v247, v239, v247
	v_exp_f32_e32 v244, v244
	v_exp_f32_e32 v245, v245
	v_exp_f32_e32 v246, v246
	v_exp_f32_e32 v247, v247
	v_add_f32_e32 v244, 1.0, v244
	v_add_f32_e32 v245, 1.0, v245
	v_add_f32_e32 v246, 1.0, v246
	v_add_f32_e32 v247, 1.0, v247
	v_rcp_f32_e32 v244, v244
	v_rcp_f32_e32 v245, v245
	v_rcp_f32_e32 v246, v246
	v_rcp_f32_e32 v247, v247
	v_mul_f32_e32 v244, v236, v244
	v_mul_f32_e32 v245, v237, v245
	v_mul_f32_e32 v246, v238, v246
	v_mul_f32_e32 v247, v239, v247
	v_mul_f32_e32 v248, v240, v244
	v_mul_f32_e32 v249, v241, v245
	v_mul_f32_e32 v250, v242, v246
	v_mul_f32_e32 v251, v243, v247
	v_mov_b32_e32 v180, v210
	v_mov_b32_e32 v181, v211
	v_cvt_pk_bf16_f32 v182, v248, v249
	v_cvt_pk_bf16_f32 v183, v250, v251
	v_add_u32_e32 v252, 1, v174
	v_mad_i64_i32 v[226:227], vcc, v252, s79, v[190:191]
	v_cmp_lt_u32_e64 s[8:9], 0, v219
	v_cmp_gt_i32_e32 vcc, s58, v252
	s_nop 1
	s_and_b64 vcc, vcc, s[8:9]
	s_and_saveexec_b64 s[10:11], vcc
	global_store_dwordx4 v[226:227], v[180:183], off sc1
	s_mov_b64 exec, s[10:11]
	v_fma_f32 v236, v88, v144, v152
	v_fma_f32 v237, v89, v145, v153
	v_fma_f32 v238, v90, v146, v154
	v_fma_f32 v239, v91, v147, v155
	v_fmac_f32_e32 v236, v104, v136
	v_fmac_f32_e32 v237, v105, v137
	v_fmac_f32_e32 v238, v106, v138
	v_fmac_f32_e32 v239, v107, v139
	v_fmac_f32_e32 v236, v120, v128
	v_fmac_f32_e32 v237, v121, v129
	v_fmac_f32_e32 v238, v122, v130
	v_fmac_f32_e32 v239, v123, v131
	v_fma_f32 v240, v80, v148, v156
	v_fma_f32 v241, v81, v149, v157
	v_fma_f32 v242, v82, v150, v158
	v_fma_f32 v243, v83, v151, v159
	v_fmac_f32_e32 v240, v96, v140
	v_fmac_f32_e32 v241, v97, v141
	v_fmac_f32_e32 v242, v98, v142
	v_fmac_f32_e32 v243, v99, v143
	v_fmac_f32_e32 v240, v112, v132
	v_fmac_f32_e32 v241, v113, v133
	v_fmac_f32_e32 v242, v114, v134
	v_fmac_f32_e32 v243, v115, v135
	v_mov_b32_e32 v228, 0xbdd2d3e8
	v_mul_f32_e32 v244, v236, v236
	v_mul_f32_e32 v245, v237, v237
	v_mul_f32_e32 v246, v238, v238
	v_mul_f32_e32 v247, v239, v239
	v_fmaak_f32 v244, v244, v228, 0xc0135761
	v_fmaak_f32 v245, v245, v228, 0xc0135761
	v_fmaak_f32 v246, v246, v228, 0xc0135761
	v_fmaak_f32 v247, v247, v228, 0xc0135761
	v_mul_f32_e32 v244, v236, v244
	v_mul_f32_e32 v245, v237, v245
	v_mul_f32_e32 v246, v238, v246
	v_mul_f32_e32 v247, v239, v247
	v_exp_f32_e32 v244, v244
	v_exp_f32_e32 v245, v245
	v_exp_f32_e32 v246, v246
	v_exp_f32_e32 v247, v247
	v_add_f32_e32 v244, 1.0, v244
	v_add_f32_e32 v245, 1.0, v245
	v_add_f32_e32 v246, 1.0, v246
	v_add_f32_e32 v247, 1.0, v247
	v_rcp_f32_e32 v244, v244
	v_rcp_f32_e32 v245, v245
	v_rcp_f32_e32 v246, v246
	v_rcp_f32_e32 v247, v247
	v_mul_f32_e32 v244, v236, v244
	v_mul_f32_e32 v245, v237, v245
	v_mul_f32_e32 v246, v238, v246
	v_mul_f32_e32 v247, v239, v247
	v_mul_f32_e32 v248, v240, v244
	v_mul_f32_e32 v249, v241, v245
	v_mul_f32_e32 v250, v242, v246
	v_mul_f32_e32 v251, v243, v247
	v_mov_b32_e32 v180, v212
	v_mov_b32_e32 v181, v213
	v_cvt_pk_bf16_f32 v182, v248, v249
	v_cvt_pk_bf16_f32 v183, v250, v251
	v_add_u32_e32 v252, 2, v174
	v_mad_i64_i32 v[226:227], vcc, v252, s79, v[190:191]
	v_cmp_gt_i32_e32 vcc, s58, v252
	s_nop 1
	s_and_saveexec_b64 s[10:11], vcc
	global_store_dwordx4 v[226:227], v[180:183], off sc1
	s_mov_b64 exec, s[10:11]
	v_fma_f32 v236, v72, v144, v152
	v_fma_f32 v237, v73, v145, v153
	v_fma_f32 v238, v74, v146, v154
	v_fma_f32 v239, v75, v147, v155
	v_fmac_f32_e32 v236, v88, v136
	v_fmac_f32_e32 v237, v89, v137
	v_fmac_f32_e32 v238, v90, v138
	v_fmac_f32_e32 v239, v91, v139
	v_fmac_f32_e32 v236, v104, v128
	v_fmac_f32_e32 v237, v105, v129
	v_fmac_f32_e32 v238, v106, v130
	v_fmac_f32_e32 v239, v107, v131
	v_fma_f32 v240, v64, v148, v156
	v_fma_f32 v241, v65, v149, v157
	v_fma_f32 v242, v66, v150, v158
	v_fma_f32 v243, v67, v151, v159
	v_fmac_f32_e32 v240, v80, v140
	v_fmac_f32_e32 v241, v81, v141
	v_fmac_f32_e32 v242, v82, v142
	v_fmac_f32_e32 v243, v83, v143
	v_fmac_f32_e32 v240, v96, v132
	v_fmac_f32_e32 v241, v97, v133
	v_fmac_f32_e32 v242, v98, v134
	v_fmac_f32_e32 v243, v99, v135
	v_mov_b32_e32 v228, 0xbdd2d3e8
	v_mul_f32_e32 v244, v236, v236
	v_mul_f32_e32 v245, v237, v237
	v_mul_f32_e32 v246, v238, v238
	v_mul_f32_e32 v247, v239, v239
	v_fmaak_f32 v244, v244, v228, 0xc0135761
	v_fmaak_f32 v245, v245, v228, 0xc0135761
	v_fmaak_f32 v246, v246, v228, 0xc0135761
	v_fmaak_f32 v247, v247, v228, 0xc0135761
	v_mul_f32_e32 v244, v236, v244
	v_mul_f32_e32 v245, v237, v245
	v_mul_f32_e32 v246, v238, v246
	v_mul_f32_e32 v247, v239, v247
	v_exp_f32_e32 v244, v244
	v_exp_f32_e32 v245, v245
	v_exp_f32_e32 v246, v246
	v_exp_f32_e32 v247, v247
	v_add_f32_e32 v244, 1.0, v244
	v_add_f32_e32 v245, 1.0, v245
	v_add_f32_e32 v246, 1.0, v246
	v_add_f32_e32 v247, 1.0, v247
	v_rcp_f32_e32 v244, v244
	v_rcp_f32_e32 v245, v245
	v_rcp_f32_e32 v246, v246
	v_rcp_f32_e32 v247, v247
	v_mul_f32_e32 v244, v236, v244
	v_mul_f32_e32 v245, v237, v245
	v_mul_f32_e32 v246, v238, v246
	v_mul_f32_e32 v247, v239, v247
	v_mul_f32_e32 v248, v240, v244
	v_mul_f32_e32 v249, v241, v245
	v_mul_f32_e32 v250, v242, v246
	v_mul_f32_e32 v251, v243, v247
	v_mov_b32_e32 v180, v214
	v_mov_b32_e32 v181, v215
	v_cvt_pk_bf16_f32 v182, v248, v249
	v_cvt_pk_bf16_f32 v183, v250, v251
	v_add_u32_e32 v252, 3, v174
	v_mad_i64_i32 v[226:227], vcc, v252, s79, v[190:191]
	v_cmp_gt_i32_e32 vcc, s58, v252
	s_nop 1
	s_and_saveexec_b64 s[10:11], vcc
	global_store_dwordx4 v[226:227], v[180:183], off sc1
	s_mov_b64 exec, s[10:11]
	v_fma_f32 v236, v56, v144, v152
	v_fma_f32 v237, v57, v145, v153
	v_fma_f32 v238, v58, v146, v154
	v_fma_f32 v239, v59, v147, v155
	v_fmac_f32_dpp v236, v12, v136 row_shr:1 row_mask:0xf bank_mask:0xf bound_ctrl:1
	v_fmac_f32_dpp v237, v13, v137 row_shr:1 row_mask:0xf bank_mask:0xf bound_ctrl:1
	v_fmac_f32_dpp v238, v14, v138 row_shr:1 row_mask:0xf bank_mask:0xf bound_ctrl:1
	v_fmac_f32_dpp v239, v15, v139 row_shr:1 row_mask:0xf bank_mask:0xf bound_ctrl:1
	v_fmac_f32_dpp v236, v72, v160 row_ror:1 row_mask:0xf bank_mask:0xf
	v_fmac_f32_dpp v237, v73, v161 row_ror:1 row_mask:0xf bank_mask:0xf
	v_fmac_f32_dpp v238, v74, v162 row_ror:1 row_mask:0xf bank_mask:0xf
	v_fmac_f32_dpp v239, v75, v163 row_ror:1 row_mask:0xf bank_mask:0xf
	v_fmac_f32_dpp v236, v24, v128 row_shr:1 row_mask:0xf bank_mask:0xf bound_ctrl:1
	v_fmac_f32_dpp v237, v25, v129 row_shr:1 row_mask:0xf bank_mask:0xf bound_ctrl:1
	v_fmac_f32_dpp v238, v26, v130 row_shr:1 row_mask:0xf bank_mask:0xf bound_ctrl:1
	v_fmac_f32_dpp v239, v27, v131 row_shr:1 row_mask:0xf bank_mask:0xf bound_ctrl:1
	v_fmac_f32_dpp v236, v88, v168 row_ror:1 row_mask:0xf bank_mask:0xf
	v_fmac_f32_dpp v237, v89, v169 row_ror:1 row_mask:0xf bank_mask:0xf
	v_fmac_f32_dpp v238, v90, v170 row_ror:1 row_mask:0xf bank_mask:0xf
	v_fmac_f32_dpp v239, v91, v171 row_ror:1 row_mask:0xf bank_mask:0xf
	v_fma_f32 v240, v48, v148, v156
	v_fma_f32 v241, v49, v149, v157
	v_fma_f32 v242, v50, v150, v158
	v_fma_f32 v243, v51, v151, v159
	v_fmac_f32_dpp v240, v0, v140 row_shr:1 row_mask:0xf bank_mask:0xf bound_ctrl:1
	v_fmac_f32_dpp v241, v1, v141 row_shr:1 row_mask:0xf bank_mask:0xf bound_ctrl:1
	v_fmac_f32_dpp v242, v2, v142 row_shr:1 row_mask:0xf bank_mask:0xf bound_ctrl:1
	v_fmac_f32_dpp v243, v3, v143 row_shr:1 row_mask:0xf bank_mask:0xf bound_ctrl:1
	v_fmac_f32_dpp v240, v64, v164 row_ror:1 row_mask:0xf bank_mask:0xf
	v_fmac_f32_dpp v241, v65, v165 row_ror:1 row_mask:0xf bank_mask:0xf
	v_fmac_f32_dpp v242, v66, v166 row_ror:1 row_mask:0xf bank_mask:0xf
	v_fmac_f32_dpp v243, v67, v167 row_ror:1 row_mask:0xf bank_mask:0xf
	v_fmac_f32_dpp v240, v16, v132 row_shr:1 row_mask:0xf bank_mask:0xf bound_ctrl:1
	v_fmac_f32_dpp v241, v17, v133 row_shr:1 row_mask:0xf bank_mask:0xf bound_ctrl:1
	v_fmac_f32_dpp v242, v18, v134 row_shr:1 row_mask:0xf bank_mask:0xf bound_ctrl:1
	v_fmac_f32_dpp v243, v19, v135 row_shr:1 row_mask:0xf bank_mask:0xf bound_ctrl:1
	v_fmac_f32_dpp v240, v80, v204 row_ror:1 row_mask:0xf bank_mask:0xf
	v_fmac_f32_dpp v241, v81, v205 row_ror:1 row_mask:0xf bank_mask:0xf
	v_fmac_f32_dpp v242, v82, v206 row_ror:1 row_mask:0xf bank_mask:0xf
	v_fmac_f32_dpp v243, v83, v207 row_ror:1 row_mask:0xf bank_mask:0xf
	v_mov_b32_e32 v228, 0xbdd2d3e8
	v_mul_f32_e32 v244, v236, v236
	v_mul_f32_e32 v245, v237, v237
	v_mul_f32_e32 v246, v238, v238
	v_mul_f32_e32 v247, v239, v239
	v_fmaak_f32 v244, v244, v228, 0xc0135761
	v_fmaak_f32 v245, v245, v228, 0xc0135761
	v_fmaak_f32 v246, v246, v228, 0xc0135761
	v_fmaak_f32 v247, v247, v228, 0xc0135761
	v_mul_f32_e32 v244, v236, v244
	v_mul_f32_e32 v245, v237, v245
	v_mul_f32_e32 v246, v238, v246
	v_mul_f32_e32 v247, v239, v247
	v_exp_f32_e32 v244, v244
	v_exp_f32_e32 v245, v245
	v_exp_f32_e32 v246, v246
	v_exp_f32_e32 v247, v247
	v_add_f32_e32 v244, 1.0, v244
	v_add_f32_e32 v245, 1.0, v245
	v_add_f32_e32 v246, 1.0, v246
	v_add_f32_e32 v247, 1.0, v247
	v_rcp_f32_e32 v244, v244
	v_rcp_f32_e32 v245, v245
	v_rcp_f32_e32 v246, v246
	v_rcp_f32_e32 v247, v247
	v_mul_f32_e32 v244, v236, v244
	v_mul_f32_e32 v245, v237, v245
	v_mul_f32_e32 v246, v238, v246
	v_mul_f32_e32 v247, v239, v247
	v_mul_f32_e32 v248, v240, v244
	v_mul_f32_e32 v249, v241, v245
	v_mul_f32_e32 v250, v242, v246
	v_mul_f32_e32 v251, v243, v247
	v_mov_b32_e32 v180, v216
	v_mov_b32_e32 v181, v217
	v_cvt_pk_bf16_f32 v182, v248, v249
	v_cvt_pk_bf16_f32 v183, v250, v251
	v_add_u32_e32 v252, 64, v174
	v_mad_i64_i32 v[226:227], vcc, v252, s79, v[190:191]
	v_cmp_gt_i32_e32 vcc, s58, v252
	s_nop 1
	s_and_saveexec_b64 s[10:11], vcc
	global_store_dwordx4 v[226:227], v[180:183], off sc1
	s_mov_b64 exec, s[10:11]
	v_fma_f32 v236, v40, v144, v152
	v_fma_f32 v237, v41, v145, v153
	v_fma_f32 v238, v42, v146, v154
	v_fma_f32 v239, v43, v147, v155
	v_fmac_f32_e32 v236, v56, v136
	v_fmac_f32_e32 v237, v57, v137
	v_fmac_f32_e32 v238, v58, v138
	v_fmac_f32_e32 v239, v59, v139
	v_fmac_f32_dpp v236, v12, v128 row_shr:1 row_mask:0xf bank_mask:0xf bound_ctrl:1
	v_fmac_f32_dpp v237, v13, v129 row_shr:1 row_mask:0xf bank_mask:0xf bound_ctrl:1
	v_fmac_f32_dpp v238, v14, v130 row_shr:1 row_mask:0xf bank_mask:0xf bound_ctrl:1
	v_fmac_f32_dpp v239, v15, v131 row_shr:1 row_mask:0xf bank_mask:0xf bound_ctrl:1
	v_fmac_f32_dpp v236, v72, v168 row_ror:1 row_mask:0xf bank_mask:0xf
	v_fmac_f32_dpp v237, v73, v169 row_ror:1 row_mask:0xf bank_mask:0xf
	v_fmac_f32_dpp v238, v74, v170 row_ror:1 row_mask:0xf bank_mask:0xf
	v_fmac_f32_dpp v239, v75, v171 row_ror:1 row_mask:0xf bank_mask:0xf
	v_fma_f32 v240, v32, v148, v156
	v_fma_f32 v241, v33, v149, v157
	v_fma_f32 v242, v34, v150, v158
	v_fma_f32 v243, v35, v151, v159
	v_fmac_f32_e32 v240, v48, v140
	v_fmac_f32_e32 v241, v49, v141
	v_fmac_f32_e32 v242, v50, v142
	v_fmac_f32_e32 v243, v51, v143
	v_fmac_f32_dpp v240, v0, v132 row_shr:1 row_mask:0xf bank_mask:0xf bound_ctrl:1
	v_fmac_f32_dpp v241, v1, v133 row_shr:1 row_mask:0xf bank_mask:0xf bound_ctrl:1
	v_fmac_f32_dpp v242, v2, v134 row_shr:1 row_mask:0xf bank_mask:0xf bound_ctrl:1
	v_fmac_f32_dpp v243, v3, v135 row_shr:1 row_mask:0xf bank_mask:0xf bound_ctrl:1
	v_fmac_f32_dpp v240, v64, v204 row_ror:1 row_mask:0xf bank_mask:0xf
	v_fmac_f32_dpp v241, v65, v205 row_ror:1 row_mask:0xf bank_mask:0xf
	v_fmac_f32_dpp v242, v66, v206 row_ror:1 row_mask:0xf bank_mask:0xf
	v_fmac_f32_dpp v243, v67, v207 row_ror:1 row_mask:0xf bank_mask:0xf
	v_mov_b32_e32 v228, 0xbdd2d3e8
	v_mul_f32_e32 v244, v236, v236
	v_mul_f32_e32 v245, v237, v237
	v_mul_f32_e32 v246, v238, v238
	v_mul_f32_e32 v247, v239, v239
	v_fmaak_f32 v244, v244, v228, 0xc0135761
	v_fmaak_f32 v245, v245, v228, 0xc0135761
	v_fmaak_f32 v246, v246, v228, 0xc0135761
	v_fmaak_f32 v247, v247, v228, 0xc0135761
	v_mul_f32_e32 v244, v236, v244
	v_mul_f32_e32 v245, v237, v245
	v_mul_f32_e32 v246, v238, v246
	v_mul_f32_e32 v247, v239, v247
	v_exp_f32_e32 v244, v244
	v_exp_f32_e32 v245, v245
	v_exp_f32_e32 v246, v246
	v_exp_f32_e32 v247, v247
	v_add_f32_e32 v244, 1.0, v244
	v_add_f32_e32 v245, 1.0, v245
	v_add_f32_e32 v246, 1.0, v246
	v_add_f32_e32 v247, 1.0, v247
	v_rcp_f32_e32 v244, v244
	v_rcp_f32_e32 v245, v245
	v_rcp_f32_e32 v246, v246
	v_rcp_f32_e32 v247, v247
	v_mul_f32_e32 v244, v236, v244
	v_mul_f32_e32 v245, v237, v245
	v_mul_f32_e32 v246, v238, v246
	v_mul_f32_e32 v247, v239, v247
	v_mul_f32_e32 v248, v240, v244
	v_mul_f32_e32 v249, v241, v245
	v_mul_f32_e32 v250, v242, v246
	v_mul_f32_e32 v251, v243, v247
	v_mov_b32_e32 v180, v220
	v_mov_b32_e32 v181, v221
	v_cvt_pk_bf16_f32 v182, v248, v249
	v_cvt_pk_bf16_f32 v183, v250, v251
	v_add_u32_e32 v252, 65, v174
	v_mad_i64_i32 v[226:227], vcc, v252, s79, v[190:191]
	v_cmp_gt_i32_e32 vcc, s58, v252
	s_nop 1
	s_and_saveexec_b64 s[10:11], vcc
	global_store_dwordx4 v[226:227], v[180:183], off sc1
	s_mov_b64 exec, s[10:11]
	v_fma_f32 v236, v24, v144, v152
	v_fma_f32 v237, v25, v145, v153
	v_fma_f32 v238, v26, v146, v154
	v_fma_f32 v239, v27, v147, v155
	v_fmac_f32_e32 v236, v40, v136
	v_fmac_f32_e32 v237, v41, v137
	v_fmac_f32_e32 v238, v42, v138
	v_fmac_f32_e32 v239, v43, v139
	v_fmac_f32_e32 v236, v56, v128
	v_fmac_f32_e32 v237, v57, v129
	v_fmac_f32_e32 v238, v58, v130
	v_fmac_f32_e32 v239, v59, v131
	v_fma_f32 v240, v16, v148, v156
	v_fma_f32 v241, v17, v149, v157
	v_fma_f32 v242, v18, v150, v158
	v_fma_f32 v243, v19, v151, v159
	v_fmac_f32_e32 v240, v32, v140
	v_fmac_f32_e32 v241, v33, v141
	v_fmac_f32_e32 v242, v34, v142
	v_fmac_f32_e32 v243, v35, v143
	v_fmac_f32_e32 v240, v48, v132
	v_fmac_f32_e32 v241, v49, v133
	v_fmac_f32_e32 v242, v50, v134
	v_fmac_f32_e32 v243, v51, v135
	v_mov_b32_e32 v228, 0xbdd2d3e8
	v_mul_f32_e32 v244, v236, v236
	v_mul_f32_e32 v245, v237, v237
	v_mul_f32_e32 v246, v238, v238
	v_mul_f32_e32 v247, v239, v239
	v_fmaak_f32 v244, v244, v228, 0xc0135761
	v_fmaak_f32 v245, v245, v228, 0xc0135761
	v_fmaak_f32 v246, v246, v228, 0xc0135761
	v_fmaak_f32 v247, v247, v228, 0xc0135761
	v_mul_f32_e32 v244, v236, v244
	v_mul_f32_e32 v245, v237, v245
	v_mul_f32_e32 v246, v238, v246
	v_mul_f32_e32 v247, v239, v247
	v_exp_f32_e32 v244, v244
	v_exp_f32_e32 v245, v245
	v_exp_f32_e32 v246, v246
	v_exp_f32_e32 v247, v247
	v_add_f32_e32 v244, 1.0, v244
	v_add_f32_e32 v245, 1.0, v245
	v_add_f32_e32 v246, 1.0, v246
	v_add_f32_e32 v247, 1.0, v247
	v_rcp_f32_e32 v244, v244
	v_rcp_f32_e32 v245, v245
	v_rcp_f32_e32 v246, v246
	v_rcp_f32_e32 v247, v247
	v_mul_f32_e32 v244, v236, v244
	v_mul_f32_e32 v245, v237, v245
	v_mul_f32_e32 v246, v238, v246
	v_mul_f32_e32 v247, v239, v247
	v_mul_f32_e32 v248, v240, v244
	v_mul_f32_e32 v249, v241, v245
	v_mul_f32_e32 v250, v242, v246
	v_mul_f32_e32 v251, v243, v247
	v_mov_b32_e32 v180, v222
	v_mov_b32_e32 v181, v223
	v_cvt_pk_bf16_f32 v182, v248, v249
	v_cvt_pk_bf16_f32 v183, v250, v251
	v_add_u32_e32 v252, 66, v174
	v_mad_i64_i32 v[226:227], vcc, v252, s79, v[190:191]
	v_cmp_gt_i32_e32 vcc, s58, v252
	s_nop 1
	s_and_saveexec_b64 s[10:11], vcc
	global_store_dwordx4 v[226:227], v[180:183], off sc1
	s_mov_b64 exec, s[10:11]
	v_fma_f32 v236, v12, v144, v152
	v_fma_f32 v237, v13, v145, v153
	v_fma_f32 v238, v14, v146, v154
	v_fma_f32 v239, v15, v147, v155
	v_fmac_f32_e32 v236, v24, v136
	v_fmac_f32_e32 v237, v25, v137
	v_fmac_f32_e32 v238, v26, v138
	v_fmac_f32_e32 v239, v27, v139
	v_fmac_f32_e32 v236, v40, v128
	v_fmac_f32_e32 v237, v41, v129
	v_fmac_f32_e32 v238, v42, v130
	v_fmac_f32_e32 v239, v43, v131
	v_fma_f32 v240, v0, v148, v156
	v_fma_f32 v241, v1, v149, v157
	v_fma_f32 v242, v2, v150, v158
	v_fma_f32 v243, v3, v151, v159
	v_fmac_f32_e32 v240, v16, v140
	v_fmac_f32_e32 v241, v17, v141
	v_fmac_f32_e32 v242, v18, v142
	v_fmac_f32_e32 v243, v19, v143
	v_fmac_f32_e32 v240, v32, v132
	v_fmac_f32_e32 v241, v33, v133
	v_fmac_f32_e32 v242, v34, v134
	v_fmac_f32_e32 v243, v35, v135
	v_mov_b32_e32 v228, 0xbdd2d3e8
	v_mul_f32_e32 v244, v236, v236
	v_mul_f32_e32 v245, v237, v237
	v_mul_f32_e32 v246, v238, v238
	v_mul_f32_e32 v247, v239, v239
	v_fmaak_f32 v244, v244, v228, 0xc0135761
	v_fmaak_f32 v245, v245, v228, 0xc0135761
	v_fmaak_f32 v246, v246, v228, 0xc0135761
	v_fmaak_f32 v247, v247, v228, 0xc0135761
	v_mul_f32_e32 v244, v236, v244
	v_mul_f32_e32 v245, v237, v245
	v_mul_f32_e32 v246, v238, v246
	v_mul_f32_e32 v247, v239, v247
	v_exp_f32_e32 v244, v244
	v_exp_f32_e32 v245, v245
	v_exp_f32_e32 v246, v246
	v_exp_f32_e32 v247, v247
	v_add_f32_e32 v244, 1.0, v244
	v_add_f32_e32 v245, 1.0, v245
	v_add_f32_e32 v246, 1.0, v246
	v_add_f32_e32 v247, 1.0, v247
	v_rcp_f32_e32 v244, v244
	v_rcp_f32_e32 v245, v245
	v_rcp_f32_e32 v246, v246
	v_rcp_f32_e32 v247, v247
	v_mul_f32_e32 v244, v236, v244
	v_mul_f32_e32 v245, v237, v245
	v_mul_f32_e32 v246, v238, v246
	v_mul_f32_e32 v247, v239, v247
	v_mul_f32_e32 v248, v240, v244
	v_mul_f32_e32 v249, v241, v245
	v_mul_f32_e32 v250, v242, v246
	v_mul_f32_e32 v251, v243, v247
	v_mov_b32_e32 v180, v224
	v_mov_b32_e32 v181, v225
	v_cvt_pk_bf16_f32 v182, v248, v249
	v_cvt_pk_bf16_f32 v183, v250, v251
	v_add_u32_e32 v252, 67, v174
	v_mad_i64_i32 v[226:227], vcc, v252, s79, v[190:191]
	v_cmp_gt_i32_e32 vcc, s58, v252
	s_nop 1
	s_and_saveexec_b64 s[10:11], vcc
	global_store_dwordx4 v[226:227], v[180:183], off sc1
	s_mov_b64 exec, s[10:11]
	s_branch .Lffn1e_done
.Lffn1e_slowall:
	v_add_u32_e32 v189, 2064, v174
	v_mul_hi_u32 v203, v189, s59
	v_lshrrev_b32_e32 v203, 7, v203
	v_mul_u32_u24_e32 v203, 0x810, v203
	v_sub_u32_e32 v189, v189, v203
	v_cmp_lt_u32_e32 vcc, 0, v189
	v_cmp_lt_u32_e64 s[8:9], 1, v189
	s_nop 1
	v_mov_b32_dpp v228, v76 row_shr:1 row_mask:0xf bank_mask:0xf bound_ctrl:1
	v_mov_b32_dpp v230, v77 row_shr:1 row_mask:0xf bank_mask:0xf bound_ctrl:1
	v_mov_b32_dpp v232, v78 row_shr:1 row_mask:0xf bank_mask:0xf bound_ctrl:1
	v_mov_b32_dpp v234, v79 row_shr:1 row_mask:0xf bank_mask:0xf bound_ctrl:1
	v_mov_b32_dpp v229, v92 row_shr:1 row_mask:0xf bank_mask:0xf bound_ctrl:1
	v_mov_b32_dpp v231, v93 row_shr:1 row_mask:0xf bank_mask:0xf bound_ctrl:1
	v_mov_b32_dpp v233, v94 row_shr:1 row_mask:0xf bank_mask:0xf bound_ctrl:1
	v_mov_b32_dpp v235, v95 row_shr:1 row_mask:0xf bank_mask:0xf bound_ctrl:1
	v_cndmask_b32_e64 v228, 0, v228, vcc
	v_cndmask_b32_e64 v229, 0, v229, s[8:9]
	v_cndmask_b32_e64 v230, 0, v230, vcc
	v_cndmask_b32_e64 v231, 0, v231, s[8:9]
	v_cndmask_b32_e64 v232, 0, v232, vcc
	v_cndmask_b32_e64 v233, 0, v233, s[8:9]
	v_cndmask_b32_e64 v234, 0, v234, vcc
	v_cndmask_b32_e64 v235, 0, v235, s[8:9]
	v_fma_f32 v236, v229, v128, v152
	v_fma_f32 v237, v231, v129, v153
	v_fma_f32 v238, v233, v130, v154
	v_fma_f32 v239, v235, v131, v155
	v_fmac_f32_e32 v236, v228, v136
	v_fmac_f32_e32 v237, v230, v137
	v_fmac_f32_e32 v238, v232, v138
	v_fmac_f32_e32 v239, v234, v139
	v_fmac_f32_e32 v236, v124, v144
	v_fmac_f32_e32 v237, v125, v145
	v_fmac_f32_e32 v238, v126, v146
	v_fmac_f32_e32 v239, v127, v147
	v_mov_b32_dpp v228, v68 row_shr:1 row_mask:0xf bank_mask:0xf bound_ctrl:1
	v_mov_b32_dpp v230, v69 row_shr:1 row_mask:0xf bank_mask:0xf bound_ctrl:1
	v_mov_b32_dpp v232, v70 row_shr:1 row_mask:0xf bank_mask:0xf bound_ctrl:1
	v_mov_b32_dpp v234, v71 row_shr:1 row_mask:0xf bank_mask:0xf bound_ctrl:1
	v_mov_b32_dpp v229, v84 row_shr:1 row_mask:0xf bank_mask:0xf bound_ctrl:1
	v_mov_b32_dpp v231, v85 row_shr:1 row_mask:0xf bank_mask:0xf bound_ctrl:1
	v_mov_b32_dpp v233, v86 row_shr:1 row_mask:0xf bank_mask:0xf bound_ctrl:1
	v_mov_b32_dpp v235, v87 row_shr:1 row_mask:0xf bank_mask:0xf bound_ctrl:1
	v_cndmask_b32_e64 v228, 0, v228, vcc
	v_cndmask_b32_e64 v229, 0, v229, s[8:9]
	v_cndmask_b32_e64 v230, 0, v230, vcc
	v_cndmask_b32_e64 v231, 0, v231, s[8:9]
	v_cndmask_b32_e64 v232, 0, v232, vcc
	v_cndmask_b32_e64 v233, 0, v233, s[8:9]
	v_cndmask_b32_e64 v234, 0, v234, vcc
	v_cndmask_b32_e64 v235, 0, v235, s[8:9]
	v_fma_f32 v240, v229, v132, v156
	v_fma_f32 v241, v231, v133, v157
	v_fma_f32 v242, v233, v134, v158
	v_fma_f32 v243, v235, v135, v159
	v_fmac_f32_e32 v240, v228, v140
	v_fmac_f32_e32 v241, v230, v141
	v_fmac_f32_e32 v242, v232, v142
	v_fmac_f32_e32 v243, v234, v143
	v_fmac_f32_e32 v240, v116, v148
	v_fmac_f32_e32 v241, v117, v149
	v_fmac_f32_e32 v242, v118, v150
	v_fmac_f32_e32 v243, v119, v151
	v_mov_b32_e32 v228, 0xbdd2d3e8
	v_mul_f32_e32 v244, v236, v236
	v_mul_f32_e32 v245, v237, v237
	v_mul_f32_e32 v246, v238, v238
	v_mul_f32_e32 v247, v239, v239
	v_fmaak_f32 v244, v244, v228, 0xc0135761
	v_fmaak_f32 v245, v245, v228, 0xc0135761
	v_fmaak_f32 v246, v246, v228, 0xc0135761
	v_fmaak_f32 v247, v247, v228, 0xc0135761
	v_mul_f32_e32 v244, v236, v244
	v_mul_f32_e32 v245, v237, v245
	v_mul_f32_e32 v246, v238, v246
	v_mul_f32_e32 v247, v239, v247
	v_exp_f32_e32 v244, v244
	v_exp_f32_e32 v245, v245
	v_exp_f32_e32 v246, v246
	v_exp_f32_e32 v247, v247
	v_add_f32_e32 v244, 1.0, v244
	v_add_f32_e32 v245, 1.0, v245
	v_add_f32_e32 v246, 1.0, v246
	v_add_f32_e32 v247, 1.0, v247
	v_rcp_f32_e32 v244, v244
	v_rcp_f32_e32 v245, v245
	v_rcp_f32_e32 v246, v246
	v_rcp_f32_e32 v247, v247
	v_mul_f32_e32 v244, v236, v244
	v_mul_f32_e32 v245, v237, v245
	v_mul_f32_e32 v246, v238, v246
	v_mul_f32_e32 v247, v239, v247
	v_mul_f32_e32 v248, v240, v244
	v_mul_f32_e32 v249, v241, v245
	v_mul_f32_e32 v250, v242, v246
	v_mul_f32_e32 v251, v243, v247
	v_cvt_pk_bf16_f32 v208, v248, v249
	v_cvt_pk_bf16_f32 v209, v250, v251
	v_add_u32_e32 v189, 2065, v174
	v_mul_hi_u32 v203, v189, s59
	v_lshrrev_b32_e32 v203, 7, v203
	v_mul_u32_u24_e32 v203, 0x810, v203
	v_sub_u32_e32 v189, v189, v203
	v_cmp_lt_u32_e32 vcc, 0, v189
	v_cmp_lt_u32_e64 s[8:9], 1, v189
	s_nop 1
	v_mov_b32_e32 v228, v124
	v_mov_b32_e32 v230, v125
	v_mov_b32_e32 v232, v126
	v_mov_b32_e32 v234, v127
	v_mov_b32_dpp v229, v76 row_shr:1 row_mask:0xf bank_mask:0xf bound_ctrl:1
	v_mov_b32_dpp v231, v77 row_shr:1 row_mask:0xf bank_mask:0xf bound_ctrl:1
	v_mov_b32_dpp v233, v78 row_shr:1 row_mask:0xf bank_mask:0xf bound_ctrl:1
	v_mov_b32_dpp v235, v79 row_shr:1 row_mask:0xf bank_mask:0xf bound_ctrl:1
	v_cndmask_b32_e64 v228, 0, v228, vcc
	v_cndmask_b32_e64 v229, 0, v229, s[8:9]
	v_cndmask_b32_e64 v230, 0, v230, vcc
	v_cndmask_b32_e64 v231, 0, v231, s[8:9]
	v_cndmask_b32_e64 v232, 0, v232, vcc
	v_cndmask_b32_e64 v233, 0, v233, s[8:9]
	v_cndmask_b32_e64 v234, 0, v234, vcc
	v_cndmask_b32_e64 v235, 0, v235, s[8:9]
	v_fma_f32 v236, v229, v128, v152
	v_fma_f32 v237, v231, v129, v153
	v_fma_f32 v238, v233, v130, v154
	v_fma_f32 v239, v235, v131, v155
	v_fmac_f32_e32 v236, v228, v136
	v_fmac_f32_e32 v237, v230, v137
	v_fmac_f32_e32 v238, v232, v138
	v_fmac_f32_e32 v239, v234, v139
	v_fmac_f32_e32 v236, v108, v144
	v_fmac_f32_e32 v237, v109, v145
	v_fmac_f32_e32 v238, v110, v146
	v_fmac_f32_e32 v239, v111, v147
	v_mov_b32_e32 v228, v116
	v_mov_b32_e32 v230, v117
	v_mov_b32_e32 v232, v118
	v_mov_b32_e32 v234, v119
	v_mov_b32_dpp v229, v68 row_shr:1 row_mask:0xf bank_mask:0xf bound_ctrl:1
	v_mov_b32_dpp v231, v69 row_shr:1 row_mask:0xf bank_mask:0xf bound_ctrl:1
	v_mov_b32_dpp v233, v70 row_shr:1 row_mask:0xf bank_mask:0xf bound_ctrl:1
	v_mov_b32_dpp v235, v71 row_shr:1 row_mask:0xf bank_mask:0xf bound_ctrl:1
	v_cndmask_b32_e64 v228, 0, v228, vcc
	v_cndmask_b32_e64 v229, 0, v229, s[8:9]
	v_cndmask_b32_e64 v230, 0, v230, vcc
	v_cndmask_b32_e64 v231, 0, v231, s[8:9]
	v_cndmask_b32_e64 v232, 0, v232, vcc
	v_cndmask_b32_e64 v233, 0, v233, s[8:9]
	v_cndmask_b32_e64 v234, 0, v234, vcc
	v_cndmask_b32_e64 v235, 0, v235, s[8:9]
	v_fma_f32 v240, v229, v132, v156
	v_fma_f32 v241, v231, v133, v157
	v_fma_f32 v242, v233, v134, v158
	v_fma_f32 v243, v235, v135, v159
	v_fmac_f32_e32 v240, v228, v140
	v_fmac_f32_e32 v241, v230, v141
	v_fmac_f32_e32 v242, v232, v142
	v_fmac_f32_e32 v243, v234, v143
	v_fmac_f32_e32 v240, v100, v148
	v_fmac_f32_e32 v241, v101, v149
	v_fmac_f32_e32 v242, v102, v150
	v_fmac_f32_e32 v243, v103, v151
	v_mov_b32_e32 v228, 0xbdd2d3e8
	v_mul_f32_e32 v244, v236, v236
	v_mul_f32_e32 v245, v237, v237
	v_mul_f32_e32 v246, v238, v238
	v_mul_f32_e32 v247, v239, v239
	v_fmaak_f32 v244, v244, v228, 0xc0135761
	v_fmaak_f32 v245, v245, v228, 0xc0135761
	v_fmaak_f32 v246, v246, v228, 0xc0135761
	v_fmaak_f32 v247, v247, v228, 0xc0135761
	v_mul_f32_e32 v244, v236, v244
	v_mul_f32_e32 v245, v237, v245
	v_mul_f32_e32 v246, v238, v246
	v_mul_f32_e32 v247, v239, v247
	v_exp_f32_e32 v244, v244
	v_exp_f32_e32 v245, v245
	v_exp_f32_e32 v246, v246
	v_exp_f32_e32 v247, v247
	v_add_f32_e32 v244, 1.0, v244
	v_add_f32_e32 v245, 1.0, v245
	v_add_f32_e32 v246, 1.0, v246
	v_add_f32_e32 v247, 1.0, v247
	v_rcp_f32_e32 v244, v244
	v_rcp_f32_e32 v245, v245
	v_rcp_f32_e32 v246, v246
	v_rcp_f32_e32 v247, v247
	v_mul_f32_e32 v244, v236, v244
	v_mul_f32_e32 v245, v237, v245
	v_mul_f32_e32 v246, v238, v246
	v_mul_f32_e32 v247, v239, v247
	v_mul_f32_e32 v248, v240, v244
	v_mul_f32_e32 v249, v241, v245
	v_mul_f32_e32 v250, v242, v246
	v_mul_f32_e32 v251, v243, v247
	v_cvt_pk_bf16_f32 v210, v248, v249
	v_cvt_pk_bf16_f32 v211, v250, v251
	v_add_u32_e32 v189, 2066, v174
	v_mul_hi_u32 v203, v189, s59
	v_lshrrev_b32_e32 v203, 7, v203
	v_mul_u32_u24_e32 v203, 0x810, v203
	v_sub_u32_e32 v189, v189, v203
	v_cmp_lt_u32_e32 vcc, 0, v189
	v_cmp_lt_u32_e64 s[8:9], 1, v189
	s_nop 1
	v_mov_b32_e32 v228, v108
	v_mov_b32_e32 v230, v109
	v_mov_b32_e32 v232, v110
	v_mov_b32_e32 v234, v111
	v_mov_b32_e32 v229, v124
	v_mov_b32_e32 v231, v125
	v_mov_b32_e32 v233, v126
	v_mov_b32_e32 v235, v127
	v_cndmask_b32_e64 v228, 0, v228, vcc
	v_cndmask_b32_e64 v229, 0, v229, s[8:9]
	v_cndmask_b32_e64 v230, 0, v230, vcc
	v_cndmask_b32_e64 v231, 0, v231, s[8:9]
	v_cndmask_b32_e64 v232, 0, v232, vcc
	v_cndmask_b32_e64 v233, 0, v233, s[8:9]
	v_cndmask_b32_e64 v234, 0, v234, vcc
	v_cndmask_b32_e64 v235, 0, v235, s[8:9]
	v_fma_f32 v236, v229, v128, v152
	v_fma_f32 v237, v231, v129, v153
	v_fma_f32 v238, v233, v130, v154
	v_fma_f32 v239, v235, v131, v155
	v_fmac_f32_e32 v236, v228, v136
	v_fmac_f32_e32 v237, v230, v137
	v_fmac_f32_e32 v238, v232, v138
	v_fmac_f32_e32 v239, v234, v139
	v_fmac_f32_e32 v236, v92, v144
	v_fmac_f32_e32 v237, v93, v145
	v_fmac_f32_e32 v238, v94, v146
	v_fmac_f32_e32 v239, v95, v147
	v_mov_b32_e32 v228, v100
	v_mov_b32_e32 v230, v101
	v_mov_b32_e32 v232, v102
	v_mov_b32_e32 v234, v103
	v_mov_b32_e32 v229, v116
	v_mov_b32_e32 v231, v117
	v_mov_b32_e32 v233, v118
	v_mov_b32_e32 v235, v119
	v_cndmask_b32_e64 v228, 0, v228, vcc
	v_cndmask_b32_e64 v229, 0, v229, s[8:9]
	v_cndmask_b32_e64 v230, 0, v230, vcc
	v_cndmask_b32_e64 v231, 0, v231, s[8:9]
	v_cndmask_b32_e64 v232, 0, v232, vcc
	v_cndmask_b32_e64 v233, 0, v233, s[8:9]
	v_cndmask_b32_e64 v234, 0, v234, vcc
	v_cndmask_b32_e64 v235, 0, v235, s[8:9]
	v_fma_f32 v240, v229, v132, v156
	v_fma_f32 v241, v231, v133, v157
	v_fma_f32 v242, v233, v134, v158
	v_fma_f32 v243, v235, v135, v159
	v_fmac_f32_e32 v240, v228, v140
	v_fmac_f32_e32 v241, v230, v141
	v_fmac_f32_e32 v242, v232, v142
	v_fmac_f32_e32 v243, v234, v143
	v_fmac_f32_e32 v240, v84, v148
	v_fmac_f32_e32 v241, v85, v149
	v_fmac_f32_e32 v242, v86, v150
	v_fmac_f32_e32 v243, v87, v151
	v_mov_b32_e32 v228, 0xbdd2d3e8
	v_mul_f32_e32 v244, v236, v236
	v_mul_f32_e32 v245, v237, v237
	v_mul_f32_e32 v246, v238, v238
	v_mul_f32_e32 v247, v239, v239
	v_fmaak_f32 v244, v244, v228, 0xc0135761
	v_fmaak_f32 v245, v245, v228, 0xc0135761
	v_fmaak_f32 v246, v246, v228, 0xc0135761
	v_fmaak_f32 v247, v247, v228, 0xc0135761
	v_mul_f32_e32 v244, v236, v244
	v_mul_f32_e32 v245, v237, v245
	v_mul_f32_e32 v246, v238, v246
	v_mul_f32_e32 v247, v239, v247
	v_exp_f32_e32 v244, v244
	v_exp_f32_e32 v245, v245
	v_exp_f32_e32 v246, v246
	v_exp_f32_e32 v247, v247
	v_add_f32_e32 v244, 1.0, v244
	v_add_f32_e32 v245, 1.0, v245
	v_add_f32_e32 v246, 1.0, v246
	v_add_f32_e32 v247, 1.0, v247
	v_rcp_f32_e32 v244, v244
	v_rcp_f32_e32 v245, v245
	v_rcp_f32_e32 v246, v246
	v_rcp_f32_e32 v247, v247
	v_mul_f32_e32 v244, v236, v244
	v_mul_f32_e32 v245, v237, v245
	v_mul_f32_e32 v246, v238, v246
	v_mul_f32_e32 v247, v239, v247
	v_mul_f32_e32 v248, v240, v244
	v_mul_f32_e32 v249, v241, v245
	v_mul_f32_e32 v250, v242, v246
	v_mul_f32_e32 v251, v243, v247
	v_cvt_pk_bf16_f32 v212, v248, v249
	v_cvt_pk_bf16_f32 v213, v250, v251
	v_add_u32_e32 v189, 2067, v174
	v_mul_hi_u32 v203, v189, s59
	v_lshrrev_b32_e32 v203, 7, v203
	v_mul_u32_u24_e32 v203, 0x810, v203
	v_sub_u32_e32 v189, v189, v203
	v_cmp_lt_u32_e32 vcc, 0, v189
	v_cmp_lt_u32_e64 s[8:9], 1, v189
	s_nop 1
	v_mov_b32_e32 v228, v92
	v_mov_b32_e32 v230, v93
	v_mov_b32_e32 v232, v94
	v_mov_b32_e32 v234, v95
	v_mov_b32_e32 v229, v108
	v_mov_b32_e32 v231, v109
	v_mov_b32_e32 v233, v110
	v_mov_b32_e32 v235, v111
	v_cndmask_b32_e64 v228, 0, v228, vcc
	v_cndmask_b32_e64 v229, 0, v229, s[8:9]
	v_cndmask_b32_e64 v230, 0, v230, vcc
	v_cndmask_b32_e64 v231, 0, v231, s[8:9]
	v_cndmask_b32_e64 v232, 0, v232, vcc
	v_cndmask_b32_e64 v233, 0, v233, s[8:9]
	v_cndmask_b32_e64 v234, 0, v234, vcc
	v_cndmask_b32_e64 v235, 0, v235, s[8:9]
	v_fma_f32 v236, v229, v128, v152
	v_fma_f32 v237, v231, v129, v153
	v_fma_f32 v238, v233, v130, v154
	v_fma_f32 v239, v235, v131, v155
	v_fmac_f32_e32 v236, v228, v136
	v_fmac_f32_e32 v237, v230, v137
	v_fmac_f32_e32 v238, v232, v138
	v_fmac_f32_e32 v239, v234, v139
	v_fmac_f32_e32 v236, v76, v144
	v_fmac_f32_e32 v237, v77, v145
	v_fmac_f32_e32 v238, v78, v146
	v_fmac_f32_e32 v239, v79, v147
	v_mov_b32_e32 v228, v84
	v_mov_b32_e32 v230, v85
	v_mov_b32_e32 v232, v86
	v_mov_b32_e32 v234, v87
	v_mov_b32_e32 v229, v100
	v_mov_b32_e32 v231, v101
	v_mov_b32_e32 v233, v102
	v_mov_b32_e32 v235, v103
	v_cndmask_b32_e64 v228, 0, v228, vcc
	v_cndmask_b32_e64 v229, 0, v229, s[8:9]
	v_cndmask_b32_e64 v230, 0, v230, vcc
	v_cndmask_b32_e64 v231, 0, v231, s[8:9]
	v_cndmask_b32_e64 v232, 0, v232, vcc
	v_cndmask_b32_e64 v233, 0, v233, s[8:9]
	v_cndmask_b32_e64 v234, 0, v234, vcc
	v_cndmask_b32_e64 v235, 0, v235, s[8:9]
	v_fma_f32 v240, v229, v132, v156
	v_fma_f32 v241, v231, v133, v157
	v_fma_f32 v242, v233, v134, v158
	v_fma_f32 v243, v235, v135, v159
	v_fmac_f32_e32 v240, v228, v140
	v_fmac_f32_e32 v241, v230, v141
	v_fmac_f32_e32 v242, v232, v142
	v_fmac_f32_e32 v243, v234, v143
	v_fmac_f32_e32 v240, v68, v148
	v_fmac_f32_e32 v241, v69, v149
	v_fmac_f32_e32 v242, v70, v150
	v_fmac_f32_e32 v243, v71, v151
	v_mov_b32_e32 v228, 0xbdd2d3e8
	v_mul_f32_e32 v244, v236, v236
	v_mul_f32_e32 v245, v237, v237
	v_mul_f32_e32 v246, v238, v238
	v_mul_f32_e32 v247, v239, v239
	v_fmaak_f32 v244, v244, v228, 0xc0135761
	v_fmaak_f32 v245, v245, v228, 0xc0135761
	v_fmaak_f32 v246, v246, v228, 0xc0135761
	v_fmaak_f32 v247, v247, v228, 0xc0135761
	v_mul_f32_e32 v244, v236, v244
	v_mul_f32_e32 v245, v237, v245
	v_mul_f32_e32 v246, v238, v246
	v_mul_f32_e32 v247, v239, v247
	v_exp_f32_e32 v244, v244
	v_exp_f32_e32 v245, v245
	v_exp_f32_e32 v246, v246
	v_exp_f32_e32 v247, v247
	v_add_f32_e32 v244, 1.0, v244
	v_add_f32_e32 v245, 1.0, v245
	v_add_f32_e32 v246, 1.0, v246
	v_add_f32_e32 v247, 1.0, v247
	v_rcp_f32_e32 v244, v244
	v_rcp_f32_e32 v245, v245
	v_rcp_f32_e32 v246, v246
	v_rcp_f32_e32 v247, v247
	v_mul_f32_e32 v244, v236, v244
	v_mul_f32_e32 v245, v237, v245
	v_mul_f32_e32 v246, v238, v246
	v_mul_f32_e32 v247, v239, v247
	v_mul_f32_e32 v248, v240, v244
	v_mul_f32_e32 v249, v241, v245
	v_mul_f32_e32 v250, v242, v246
	v_mul_f32_e32 v251, v243, v247
	v_cvt_pk_bf16_f32 v214, v248, v249
	v_cvt_pk_bf16_f32 v215, v250, v251
	v_add_u32_e32 v189, 2128, v174
	v_mul_hi_u32 v203, v189, s59
	v_lshrrev_b32_e32 v203, 7, v203
	v_mul_u32_u24_e32 v203, 0x810, v203
	v_sub_u32_e32 v189, v189, v203
	v_cmp_lt_u32_e32 vcc, 0, v189
	v_cmp_lt_u32_e64 s[8:9], 1, v189
	s_nop 1
	v_mov_b32_dpp v228, v76 row_ror:1 row_mask:0xf bank_mask:0xf
	v_mov_b32_dpp v230, v77 row_ror:1 row_mask:0xf bank_mask:0xf
	v_mov_b32_dpp v232, v78 row_ror:1 row_mask:0xf bank_mask:0xf
	v_mov_b32_dpp v234, v79 row_ror:1 row_mask:0xf bank_mask:0xf
	v_mov_b32_dpp v228, v4 row_shr:1 row_mask:0xf bank_mask:0xf
	v_mov_b32_dpp v230, v5 row_shr:1 row_mask:0xf bank_mask:0xf
	v_mov_b32_dpp v232, v6 row_shr:1 row_mask:0xf bank_mask:0xf
	v_mov_b32_dpp v234, v7 row_shr:1 row_mask:0xf bank_mask:0xf
	v_mov_b32_dpp v229, v92 row_ror:1 row_mask:0xf bank_mask:0xf
	v_mov_b32_dpp v231, v93 row_ror:1 row_mask:0xf bank_mask:0xf
	v_mov_b32_dpp v233, v94 row_ror:1 row_mask:0xf bank_mask:0xf
	v_mov_b32_dpp v235, v95 row_ror:1 row_mask:0xf bank_mask:0xf
	v_mov_b32_dpp v229, v28 row_shr:1 row_mask:0xf bank_mask:0xf
	v_mov_b32_dpp v231, v29 row_shr:1 row_mask:0xf bank_mask:0xf
	v_mov_b32_dpp v233, v30 row_shr:1 row_mask:0xf bank_mask:0xf
	v_mov_b32_dpp v235, v31 row_shr:1 row_mask:0xf bank_mask:0xf
	v_cndmask_b32_e64 v228, 0, v228, vcc
	v_cndmask_b32_e64 v229, 0, v229, s[8:9]
	v_cndmask_b32_e64 v230, 0, v230, vcc
	v_cndmask_b32_e64 v231, 0, v231, s[8:9]
	v_cndmask_b32_e64 v232, 0, v232, vcc
	v_cndmask_b32_e64 v233, 0, v233, s[8:9]
	v_cndmask_b32_e64 v234, 0, v234, vcc
	v_cndmask_b32_e64 v235, 0, v235, s[8:9]
	v_fma_f32 v236, v229, v128, v152
	v_fma_f32 v237, v231, v129, v153
	v_fma_f32 v238, v233, v130, v154
	v_fma_f32 v239, v235, v131, v155
	v_fmac_f32_e32 v236, v228, v136
	v_fmac_f32_e32 v237, v230, v137
	v_fmac_f32_e32 v238, v232, v138
	v_fmac_f32_e32 v239, v234, v139
	v_fmac_f32_e32 v236, v60, v144
	v_fmac_f32_e32 v237, v61, v145
	v_fmac_f32_e32 v238, v62, v146
	v_fmac_f32_e32 v239, v63, v147
	v_mov_b32_dpp v228, v68 row_ror:1 row_mask:0xf bank_mask:0xf
	v_mov_b32_dpp v230, v69 row_ror:1 row_mask:0xf bank_mask:0xf
	v_mov_b32_dpp v232, v70 row_ror:1 row_mask:0xf bank_mask:0xf
	v_mov_b32_dpp v234, v71 row_ror:1 row_mask:0xf bank_mask:0xf
	v_mov_b32_dpp v228, v8 row_shr:1 row_mask:0xf bank_mask:0xf
	v_mov_b32_dpp v230, v9 row_shr:1 row_mask:0xf bank_mask:0xf
	v_mov_b32_dpp v232, v10 row_shr:1 row_mask:0xf bank_mask:0xf
	v_mov_b32_dpp v234, v11 row_shr:1 row_mask:0xf bank_mask:0xf
	v_mov_b32_dpp v229, v84 row_ror:1 row_mask:0xf bank_mask:0xf
	v_mov_b32_dpp v231, v85 row_ror:1 row_mask:0xf bank_mask:0xf
	v_mov_b32_dpp v233, v86 row_ror:1 row_mask:0xf bank_mask:0xf
	v_mov_b32_dpp v235, v87 row_ror:1 row_mask:0xf bank_mask:0xf
	v_mov_b32_dpp v229, v20 row_shr:1 row_mask:0xf bank_mask:0xf
	v_mov_b32_dpp v231, v21 row_shr:1 row_mask:0xf bank_mask:0xf
	v_mov_b32_dpp v233, v22 row_shr:1 row_mask:0xf bank_mask:0xf
	v_mov_b32_dpp v235, v23 row_shr:1 row_mask:0xf bank_mask:0xf
	v_cndmask_b32_e64 v228, 0, v228, vcc
	v_cndmask_b32_e64 v229, 0, v229, s[8:9]
	v_cndmask_b32_e64 v230, 0, v230, vcc
	v_cndmask_b32_e64 v231, 0, v231, s[8:9]
	v_cndmask_b32_e64 v232, 0, v232, vcc
	v_cndmask_b32_e64 v233, 0, v233, s[8:9]
	v_cndmask_b32_e64 v234, 0, v234, vcc
	v_cndmask_b32_e64 v235, 0, v235, s[8:9]
	v_fma_f32 v240, v229, v132, v156
	v_fma_f32 v241, v231, v133, v157
	v_fma_f32 v242, v233, v134, v158
	v_fma_f32 v243, v235, v135, v159
	v_fmac_f32_e32 v240, v228, v140
	v_fmac_f32_e32 v241, v230, v141
	v_fmac_f32_e32 v242, v232, v142
	v_fmac_f32_e32 v243, v234, v143
	v_fmac_f32_e32 v240, v52, v148
	v_fmac_f32_e32 v241, v53, v149
	v_fmac_f32_e32 v242, v54, v150
	v_fmac_f32_e32 v243, v55, v151
	v_mov_b32_e32 v228, 0xbdd2d3e8
	v_mul_f32_e32 v244, v236, v236
	v_mul_f32_e32 v245, v237, v237
	v_mul_f32_e32 v246, v238, v238
	v_mul_f32_e32 v247, v239, v239
	v_fmaak_f32 v244, v244, v228, 0xc0135761
	v_fmaak_f32 v245, v245, v228, 0xc0135761
	v_fmaak_f32 v246, v246, v228, 0xc0135761
	v_fmaak_f32 v247, v247, v228, 0xc0135761
	v_mul_f32_e32 v244, v236, v244
	v_mul_f32_e32 v245, v237, v245
	v_mul_f32_e32 v246, v238, v246
	v_mul_f32_e32 v247, v239, v247
	v_exp_f32_e32 v244, v244
	v_exp_f32_e32 v245, v245
	v_exp_f32_e32 v246, v246
	v_exp_f32_e32 v247, v247
	v_add_f32_e32 v244, 1.0, v244
	v_add_f32_e32 v245, 1.0, v245
	v_add_f32_e32 v246, 1.0, v246
	v_add_f32_e32 v247, 1.0, v247
	v_rcp_f32_e32 v244, v244
	v_rcp_f32_e32 v245, v245
	v_rcp_f32_e32 v246, v246
	v_rcp_f32_e32 v247, v247
	v_mul_f32_e32 v244, v236, v244
	v_mul_f32_e32 v245, v237, v245
	v_mul_f32_e32 v246, v238, v246
	v_mul_f32_e32 v247, v239, v247
	v_mul_f32_e32 v248, v240, v244
	v_mul_f32_e32 v249, v241, v245
	v_mul_f32_e32 v250, v242, v246
	v_mul_f32_e32 v251, v243, v247
	v_cvt_pk_bf16_f32 v216, v248, v249
	v_cvt_pk_bf16_f32 v217, v250, v251
	v_add_u32_e32 v189, 2129, v174
	v_mul_hi_u32 v203, v189, s59
	v_lshrrev_b32_e32 v203, 7, v203
	v_mul_u32_u24_e32 v203, 0x810, v203
	v_sub_u32_e32 v189, v189, v203
	v_cmp_lt_u32_e32 vcc, 0, v189
	v_cmp_lt_u32_e64 s[8:9], 1, v189
	s_nop 1
	v_mov_b32_e32 v228, v60
	v_mov_b32_e32 v230, v61
	v_mov_b32_e32 v232, v62
	v_mov_b32_e32 v234, v63
	v_mov_b32_dpp v229, v76 row_ror:1 row_mask:0xf bank_mask:0xf
	v_mov_b32_dpp v231, v77 row_ror:1 row_mask:0xf bank_mask:0xf
	v_mov_b32_dpp v233, v78 row_ror:1 row_mask:0xf bank_mask:0xf
	v_mov_b32_dpp v235, v79 row_ror:1 row_mask:0xf bank_mask:0xf
	v_mov_b32_dpp v229, v4 row_shr:1 row_mask:0xf bank_mask:0xf
	v_mov_b32_dpp v231, v5 row_shr:1 row_mask:0xf bank_mask:0xf
	v_mov_b32_dpp v233, v6 row_shr:1 row_mask:0xf bank_mask:0xf
	v_mov_b32_dpp v235, v7 row_shr:1 row_mask:0xf bank_mask:0xf
	v_cndmask_b32_e64 v228, 0, v228, vcc
	v_cndmask_b32_e64 v229, 0, v229, s[8:9]
	v_cndmask_b32_e64 v230, 0, v230, vcc
	v_cndmask_b32_e64 v231, 0, v231, s[8:9]
	v_cndmask_b32_e64 v232, 0, v232, vcc
	v_cndmask_b32_e64 v233, 0, v233, s[8:9]
	v_cndmask_b32_e64 v234, 0, v234, vcc
	v_cndmask_b32_e64 v235, 0, v235, s[8:9]
	v_fma_f32 v236, v229, v128, v152
	v_fma_f32 v237, v231, v129, v153
	v_fma_f32 v238, v233, v130, v154
	v_fma_f32 v239, v235, v131, v155
	v_fmac_f32_e32 v236, v228, v136
	v_fmac_f32_e32 v237, v230, v137
	v_fmac_f32_e32 v238, v232, v138
	v_fmac_f32_e32 v239, v234, v139
	v_fmac_f32_e32 v236, v44, v144
	v_fmac_f32_e32 v237, v45, v145
	v_fmac_f32_e32 v238, v46, v146
	v_fmac_f32_e32 v239, v47, v147
	v_mov_b32_e32 v228, v52
	v_mov_b32_e32 v230, v53
	v_mov_b32_e32 v232, v54
	v_mov_b32_e32 v234, v55
	v_mov_b32_dpp v229, v68 row_ror:1 row_mask:0xf bank_mask:0xf
	v_mov_b32_dpp v231, v69 row_ror:1 row_mask:0xf bank_mask:0xf
	v_mov_b32_dpp v233, v70 row_ror:1 row_mask:0xf bank_mask:0xf
	v_mov_b32_dpp v235, v71 row_ror:1 row_mask:0xf bank_mask:0xf
	v_mov_b32_dpp v229, v8 row_shr:1 row_mask:0xf bank_mask:0xf
	v_mov_b32_dpp v231, v9 row_shr:1 row_mask:0xf bank_mask:0xf
	v_mov_b32_dpp v233, v10 row_shr:1 row_mask:0xf bank_mask:0xf
	v_mov_b32_dpp v235, v11 row_shr:1 row_mask:0xf bank_mask:0xf
	v_cndmask_b32_e64 v228, 0, v228, vcc
	v_cndmask_b32_e64 v229, 0, v229, s[8:9]
	v_cndmask_b32_e64 v230, 0, v230, vcc
	v_cndmask_b32_e64 v231, 0, v231, s[8:9]
	v_cndmask_b32_e64 v232, 0, v232, vcc
	v_cndmask_b32_e64 v233, 0, v233, s[8:9]
	v_cndmask_b32_e64 v234, 0, v234, vcc
	v_cndmask_b32_e64 v235, 0, v235, s[8:9]
	v_fma_f32 v240, v229, v132, v156
	v_fma_f32 v241, v231, v133, v157
	v_fma_f32 v242, v233, v134, v158
	v_fma_f32 v243, v235, v135, v159
	v_fmac_f32_e32 v240, v228, v140
	v_fmac_f32_e32 v241, v230, v141
	v_fmac_f32_e32 v242, v232, v142
	v_fmac_f32_e32 v243, v234, v143
	v_fmac_f32_e32 v240, v36, v148
	v_fmac_f32_e32 v241, v37, v149
	v_fmac_f32_e32 v242, v38, v150
	v_fmac_f32_e32 v243, v39, v151
	v_mov_b32_e32 v228, 0xbdd2d3e8
	v_mul_f32_e32 v244, v236, v236
	v_mul_f32_e32 v245, v237, v237
	v_mul_f32_e32 v246, v238, v238
	v_mul_f32_e32 v247, v239, v239
	v_fmaak_f32 v244, v244, v228, 0xc0135761
	v_fmaak_f32 v245, v245, v228, 0xc0135761
	v_fmaak_f32 v246, v246, v228, 0xc0135761
	v_fmaak_f32 v247, v247, v228, 0xc0135761
	v_mul_f32_e32 v244, v236, v244
	v_mul_f32_e32 v245, v237, v245
	v_mul_f32_e32 v246, v238, v246
	v_mul_f32_e32 v247, v239, v247
	v_exp_f32_e32 v244, v244
	v_exp_f32_e32 v245, v245
	v_exp_f32_e32 v246, v246
	v_exp_f32_e32 v247, v247
	v_add_f32_e32 v244, 1.0, v244
	v_add_f32_e32 v245, 1.0, v245
	v_add_f32_e32 v246, 1.0, v246
	v_add_f32_e32 v247, 1.0, v247
	v_rcp_f32_e32 v244, v244
	v_rcp_f32_e32 v245, v245
	v_rcp_f32_e32 v246, v246
	v_rcp_f32_e32 v247, v247
	v_mul_f32_e32 v244, v236, v244
	v_mul_f32_e32 v245, v237, v245
	v_mul_f32_e32 v246, v238, v246
	v_mul_f32_e32 v247, v239, v247
	v_mul_f32_e32 v248, v240, v244
	v_mul_f32_e32 v249, v241, v245
	v_mul_f32_e32 v250, v242, v246
	v_mul_f32_e32 v251, v243, v247
	v_cvt_pk_bf16_f32 v220, v248, v249
	v_cvt_pk_bf16_f32 v221, v250, v251
	v_add_u32_e32 v189, 2130, v174
	v_mul_hi_u32 v203, v189, s59
	v_lshrrev_b32_e32 v203, 7, v203
	v_mul_u32_u24_e32 v203, 0x810, v203
	v_sub_u32_e32 v189, v189, v203
	v_cmp_lt_u32_e32 vcc, 0, v189
	v_cmp_lt_u32_e64 s[8:9], 1, v189
	s_nop 1
	v_mov_b32_e32 v228, v44
	v_mov_b32_e32 v230, v45
	v_mov_b32_e32 v232, v46
	v_mov_b32_e32 v234, v47
	v_mov_b32_e32 v229, v60
	v_mov_b32_e32 v231, v61
	v_mov_b32_e32 v233, v62
	v_mov_b32_e32 v235, v63
	v_cndmask_b32_e64 v228, 0, v228, vcc
	v_cndmask_b32_e64 v229, 0, v229, s[8:9]
	v_cndmask_b32_e64 v230, 0, v230, vcc
	v_cndmask_b32_e64 v231, 0, v231, s[8:9]
	v_cndmask_b32_e64 v232, 0, v232, vcc
	v_cndmask_b32_e64 v233, 0, v233, s[8:9]
	v_cndmask_b32_e64 v234, 0, v234, vcc
	v_cndmask_b32_e64 v235, 0, v235, s[8:9]
	v_fma_f32 v236, v229, v128, v152
	v_fma_f32 v237, v231, v129, v153
	v_fma_f32 v238, v233, v130, v154
	v_fma_f32 v239, v235, v131, v155
	v_fmac_f32_e32 v236, v228, v136
	v_fmac_f32_e32 v237, v230, v137
	v_fmac_f32_e32 v238, v232, v138
	v_fmac_f32_e32 v239, v234, v139
	v_fmac_f32_e32 v236, v28, v144
	v_fmac_f32_e32 v237, v29, v145
	v_fmac_f32_e32 v238, v30, v146
	v_fmac_f32_e32 v239, v31, v147
	v_mov_b32_e32 v228, v36
	v_mov_b32_e32 v230, v37
	v_mov_b32_e32 v232, v38
	v_mov_b32_e32 v234, v39
	v_mov_b32_e32 v229, v52
	v_mov_b32_e32 v231, v53
	v_mov_b32_e32 v233, v54
	v_mov_b32_e32 v235, v55
	v_cndmask_b32_e64 v228, 0, v228, vcc
	v_cndmask_b32_e64 v229, 0, v229, s[8:9]
	v_cndmask_b32_e64 v230, 0, v230, vcc
	v_cndmask_b32_e64 v231, 0, v231, s[8:9]
	v_cndmask_b32_e64 v232, 0, v232, vcc
	v_cndmask_b32_e64 v233, 0, v233, s[8:9]
	v_cndmask_b32_e64 v234, 0, v234, vcc
	v_cndmask_b32_e64 v235, 0, v235, s[8:9]
	v_fma_f32 v240, v229, v132, v156
	v_fma_f32 v241, v231, v133, v157
	v_fma_f32 v242, v233, v134, v158
	v_fma_f32 v243, v235, v135, v159
	v_fmac_f32_e32 v240, v228, v140
	v_fmac_f32_e32 v241, v230, v141
	v_fmac_f32_e32 v242, v232, v142
	v_fmac_f32_e32 v243, v234, v143
	v_fmac_f32_e32 v240, v20, v148
	v_fmac_f32_e32 v241, v21, v149
	v_fmac_f32_e32 v242, v22, v150
	v_fmac_f32_e32 v243, v23, v151
	v_mov_b32_e32 v228, 0xbdd2d3e8
	v_mul_f32_e32 v244, v236, v236
	v_mul_f32_e32 v245, v237, v237
	v_mul_f32_e32 v246, v238, v238
	v_mul_f32_e32 v247, v239, v239
	v_fmaak_f32 v244, v244, v228, 0xc0135761
	v_fmaak_f32 v245, v245, v228, 0xc0135761
	v_fmaak_f32 v246, v246, v228, 0xc0135761
	v_fmaak_f32 v247, v247, v228, 0xc0135761
	v_mul_f32_e32 v244, v236, v244
	v_mul_f32_e32 v245, v237, v245
	v_mul_f32_e32 v246, v238, v246
	v_mul_f32_e32 v247, v239, v247
	v_exp_f32_e32 v244, v244
	v_exp_f32_e32 v245, v245
	v_exp_f32_e32 v246, v246
	v_exp_f32_e32 v247, v247
	v_add_f32_e32 v244, 1.0, v244
	v_add_f32_e32 v245, 1.0, v245
	v_add_f32_e32 v246, 1.0, v246
	v_add_f32_e32 v247, 1.0, v247
	v_rcp_f32_e32 v244, v244
	v_rcp_f32_e32 v245, v245
	v_rcp_f32_e32 v246, v246
	v_rcp_f32_e32 v247, v247
	v_mul_f32_e32 v244, v236, v244
	v_mul_f32_e32 v245, v237, v245
	v_mul_f32_e32 v246, v238, v246
	v_mul_f32_e32 v247, v239, v247
	v_mul_f32_e32 v248, v240, v244
	v_mul_f32_e32 v249, v241, v245
	v_mul_f32_e32 v250, v242, v246
	v_mul_f32_e32 v251, v243, v247
	v_cvt_pk_bf16_f32 v222, v248, v249
	v_cvt_pk_bf16_f32 v223, v250, v251
	v_add_u32_e32 v189, 2131, v174
	v_mul_hi_u32 v203, v189, s59
	v_lshrrev_b32_e32 v203, 7, v203
	v_mul_u32_u24_e32 v203, 0x810, v203
	v_sub_u32_e32 v189, v189, v203
	v_cmp_lt_u32_e32 vcc, 0, v189
	v_cmp_lt_u32_e64 s[8:9], 1, v189
	s_nop 1
	v_mov_b32_e32 v228, v28
	v_mov_b32_e32 v230, v29
	v_mov_b32_e32 v232, v30
	v_mov_b32_e32 v234, v31
	v_mov_b32_e32 v229, v44
	v_mov_b32_e32 v231, v45
	v_mov_b32_e32 v233, v46
	v_mov_b32_e32 v235, v47
	v_cndmask_b32_e64 v228, 0, v228, vcc
	v_cndmask_b32_e64 v229, 0, v229, s[8:9]
	v_cndmask_b32_e64 v230, 0, v230, vcc
	v_cndmask_b32_e64 v231, 0, v231, s[8:9]
	v_cndmask_b32_e64 v232, 0, v232, vcc
	v_cndmask_b32_e64 v233, 0, v233, s[8:9]
	v_cndmask_b32_e64 v234, 0, v234, vcc
	v_cndmask_b32_e64 v235, 0, v235, s[8:9]
	v_fma_f32 v236, v229, v128, v152
	v_fma_f32 v237, v231, v129, v153
	v_fma_f32 v238, v233, v130, v154
	v_fma_f32 v239, v235, v131, v155
	v_fmac_f32_e32 v236, v228, v136
	v_fmac_f32_e32 v237, v230, v137
	v_fmac_f32_e32 v238, v232, v138
	v_fmac_f32_e32 v239, v234, v139
	v_fmac_f32_e32 v236, v4, v144
	v_fmac_f32_e32 v237, v5, v145
	v_fmac_f32_e32 v238, v6, v146
	v_fmac_f32_e32 v239, v7, v147
	v_mov_b32_e32 v228, v20
	v_mov_b32_e32 v230, v21
	v_mov_b32_e32 v232, v22
	v_mov_b32_e32 v234, v23
	v_mov_b32_e32 v229, v36
	v_mov_b32_e32 v231, v37
	v_mov_b32_e32 v233, v38
	v_mov_b32_e32 v235, v39
	v_cndmask_b32_e64 v228, 0, v228, vcc
	v_cndmask_b32_e64 v229, 0, v229, s[8:9]
	v_cndmask_b32_e64 v230, 0, v230, vcc
	v_cndmask_b32_e64 v231, 0, v231, s[8:9]
	v_cndmask_b32_e64 v232, 0, v232, vcc
	v_cndmask_b32_e64 v233, 0, v233, s[8:9]
	v_cndmask_b32_e64 v234, 0, v234, vcc
	v_cndmask_b32_e64 v235, 0, v235, s[8:9]
	v_fma_f32 v240, v229, v132, v156
	v_fma_f32 v241, v231, v133, v157
	v_fma_f32 v242, v233, v134, v158
	v_fma_f32 v243, v235, v135, v159
	v_fmac_f32_e32 v240, v228, v140
	v_fmac_f32_e32 v241, v230, v141
	v_fmac_f32_e32 v242, v232, v142
	v_fmac_f32_e32 v243, v234, v143
	v_fmac_f32_e32 v240, v8, v148
	v_fmac_f32_e32 v241, v9, v149
	v_fmac_f32_e32 v242, v10, v150
	v_fmac_f32_e32 v243, v11, v151
	v_mov_b32_e32 v228, 0xbdd2d3e8
	v_mul_f32_e32 v244, v236, v236
	v_mul_f32_e32 v245, v237, v237
	v_mul_f32_e32 v246, v238, v238
	v_mul_f32_e32 v247, v239, v239
	v_fmaak_f32 v244, v244, v228, 0xc0135761
	v_fmaak_f32 v245, v245, v228, 0xc0135761
	v_fmaak_f32 v246, v246, v228, 0xc0135761
	v_fmaak_f32 v247, v247, v228, 0xc0135761
	v_mul_f32_e32 v244, v236, v244
	v_mul_f32_e32 v245, v237, v245
	v_mul_f32_e32 v246, v238, v246
	v_mul_f32_e32 v247, v239, v247
	v_exp_f32_e32 v244, v244
	v_exp_f32_e32 v245, v245
	v_exp_f32_e32 v246, v246
	v_exp_f32_e32 v247, v247
	v_add_f32_e32 v244, 1.0, v244
	v_add_f32_e32 v245, 1.0, v245
	v_add_f32_e32 v246, 1.0, v246
	v_add_f32_e32 v247, 1.0, v247
	v_rcp_f32_e32 v244, v244
	v_rcp_f32_e32 v245, v245
	v_rcp_f32_e32 v246, v246
	v_rcp_f32_e32 v247, v247
	v_mul_f32_e32 v244, v236, v244
	v_mul_f32_e32 v245, v237, v245
	v_mul_f32_e32 v246, v238, v246
	v_mul_f32_e32 v247, v239, v247
	v_mul_f32_e32 v248, v240, v244
	v_mul_f32_e32 v249, v241, v245
	v_mul_f32_e32 v250, v242, v246
	v_mul_f32_e32 v251, v243, v247
	v_cvt_pk_bf16_f32 v224, v248, v249
	v_cvt_pk_bf16_f32 v225, v250, v251
	v_add_u32_e32 v203, 0x20000, v172
	ds_read_b128 v[128:131], v203 offset:16
	ds_read_b128 v[132:135], v203 offset:528
	ds_read_b128 v[136:139], v203 offset:1040
	ds_read_b128 v[140:143], v203 offset:1552
	ds_read_b128 v[144:147], v203 offset:2064
	ds_read_b128 v[148:151], v203 offset:2576
	ds_read_b128 v[152:155], v203 offset:3088
	ds_read_b128 v[156:159], v203 offset:3600
	s_waitcnt lgkmcnt(0)
	v_add_u32_e32 v189, 2064, v174
	v_mul_hi_u32 v203, v189, s59
	v_lshrrev_b32_e32 v203, 7, v203
	v_mul_u32_u24_e32 v203, 0x810, v203
	v_sub_u32_e32 v189, v189, v203
	v_cmp_lt_u32_e32 vcc, 0, v189
	v_cmp_lt_u32_e64 s[8:9], 1, v189
	s_nop 1
	v_mov_b32_dpp v228, v72 row_shr:1 row_mask:0xf bank_mask:0xf bound_ctrl:1
	v_mov_b32_dpp v230, v73 row_shr:1 row_mask:0xf bank_mask:0xf bound_ctrl:1
	v_mov_b32_dpp v232, v74 row_shr:1 row_mask:0xf bank_mask:0xf bound_ctrl:1
	v_mov_b32_dpp v234, v75 row_shr:1 row_mask:0xf bank_mask:0xf bound_ctrl:1
	v_mov_b32_dpp v229, v88 row_shr:1 row_mask:0xf bank_mask:0xf bound_ctrl:1
	v_mov_b32_dpp v231, v89 row_shr:1 row_mask:0xf bank_mask:0xf bound_ctrl:1
	v_mov_b32_dpp v233, v90 row_shr:1 row_mask:0xf bank_mask:0xf bound_ctrl:1
	v_mov_b32_dpp v235, v91 row_shr:1 row_mask:0xf bank_mask:0xf bound_ctrl:1
	v_cndmask_b32_e64 v228, 0, v228, vcc
	v_cndmask_b32_e64 v229, 0, v229, s[8:9]
	v_cndmask_b32_e64 v230, 0, v230, vcc
	v_cndmask_b32_e64 v231, 0, v231, s[8:9]
	v_cndmask_b32_e64 v232, 0, v232, vcc
	v_cndmask_b32_e64 v233, 0, v233, s[8:9]
	v_cndmask_b32_e64 v234, 0, v234, vcc
	v_cndmask_b32_e64 v235, 0, v235, s[8:9]
	v_fma_f32 v236, v229, v128, v152
	v_fma_f32 v237, v231, v129, v153
	v_fma_f32 v238, v233, v130, v154
	v_fma_f32 v239, v235, v131, v155
	v_fmac_f32_e32 v236, v228, v136
	v_fmac_f32_e32 v237, v230, v137
	v_fmac_f32_e32 v238, v232, v138
	v_fmac_f32_e32 v239, v234, v139
	v_fmac_f32_e32 v236, v120, v144
	v_fmac_f32_e32 v237, v121, v145
	v_fmac_f32_e32 v238, v122, v146
	v_fmac_f32_e32 v239, v123, v147
	v_mov_b32_dpp v228, v64 row_shr:1 row_mask:0xf bank_mask:0xf bound_ctrl:1
	v_mov_b32_dpp v230, v65 row_shr:1 row_mask:0xf bank_mask:0xf bound_ctrl:1
	v_mov_b32_dpp v232, v66 row_shr:1 row_mask:0xf bank_mask:0xf bound_ctrl:1
	v_mov_b32_dpp v234, v67 row_shr:1 row_mask:0xf bank_mask:0xf bound_ctrl:1
	v_mov_b32_dpp v229, v80 row_shr:1 row_mask:0xf bank_mask:0xf bound_ctrl:1
	v_mov_b32_dpp v231, v81 row_shr:1 row_mask:0xf bank_mask:0xf bound_ctrl:1
	v_mov_b32_dpp v233, v82 row_shr:1 row_mask:0xf bank_mask:0xf bound_ctrl:1
	v_mov_b32_dpp v235, v83 row_shr:1 row_mask:0xf bank_mask:0xf bound_ctrl:1
	v_cndmask_b32_e64 v228, 0, v228, vcc
	v_cndmask_b32_e64 v229, 0, v229, s[8:9]
	v_cndmask_b32_e64 v230, 0, v230, vcc
	v_cndmask_b32_e64 v231, 0, v231, s[8:9]
	v_cndmask_b32_e64 v232, 0, v232, vcc
	v_cndmask_b32_e64 v233, 0, v233, s[8:9]
	v_cndmask_b32_e64 v234, 0, v234, vcc
	v_cndmask_b32_e64 v235, 0, v235, s[8:9]
	v_fma_f32 v240, v229, v132, v156
	v_fma_f32 v241, v231, v133, v157
	v_fma_f32 v242, v233, v134, v158
	v_fma_f32 v243, v235, v135, v159
	v_fmac_f32_e32 v240, v228, v140
	v_fmac_f32_e32 v241, v230, v141
	v_fmac_f32_e32 v242, v232, v142
	v_fmac_f32_e32 v243, v234, v143
	v_fmac_f32_e32 v240, v112, v148
	v_fmac_f32_e32 v241, v113, v149
	v_fmac_f32_e32 v242, v114, v150
	v_fmac_f32_e32 v243, v115, v151
	v_mov_b32_e32 v228, 0xbdd2d3e8
	v_mul_f32_e32 v244, v236, v236
	v_mul_f32_e32 v245, v237, v237
	v_mul_f32_e32 v246, v238, v238
	v_mul_f32_e32 v247, v239, v239
	v_fmaak_f32 v244, v244, v228, 0xc0135761
	v_fmaak_f32 v245, v245, v228, 0xc0135761
	v_fmaak_f32 v246, v246, v228, 0xc0135761
	v_fmaak_f32 v247, v247, v228, 0xc0135761
	v_mul_f32_e32 v244, v236, v244
	v_mul_f32_e32 v245, v237, v245
	v_mul_f32_e32 v246, v238, v246
	v_mul_f32_e32 v247, v239, v247
	v_exp_f32_e32 v244, v244
	v_exp_f32_e32 v245, v245
	v_exp_f32_e32 v246, v246
	v_exp_f32_e32 v247, v247
	v_add_f32_e32 v244, 1.0, v244
	v_add_f32_e32 v245, 1.0, v245
	v_add_f32_e32 v246, 1.0, v246
	v_add_f32_e32 v247, 1.0, v247
	v_rcp_f32_e32 v244, v244
	v_rcp_f32_e32 v245, v245
	v_rcp_f32_e32 v246, v246
	v_rcp_f32_e32 v247, v247
	v_mul_f32_e32 v244, v236, v244
	v_mul_f32_e32 v245, v237, v245
	v_mul_f32_e32 v246, v238, v246
	v_mul_f32_e32 v247, v239, v247
	v_mul_f32_e32 v248, v240, v244
	v_mul_f32_e32 v249, v241, v245
	v_mul_f32_e32 v250, v242, v246
	v_mul_f32_e32 v251, v243, v247
	v_mov_b32_e32 v180, v208
	v_mov_b32_e32 v181, v209
	v_cvt_pk_bf16_f32 v182, v248, v249
	v_cvt_pk_bf16_f32 v183, v250, v251
	v_add_u32_e32 v252, 0, v174
	v_mad_i64_i32 v[226:227], vcc, v252, s79, v[190:191]
	v_cmp_lt_u32_e64 s[8:9], 0, v219
	v_cmp_gt_i32_e32 vcc, s58, v252
	s_nop 1
	s_and_b64 vcc, vcc, s[8:9]
	s_and_saveexec_b64 s[10:11], vcc
	global_store_dwordx4 v[226:227], v[180:183], off sc1
	s_mov_b64 exec, s[10:11]
	v_add_u32_e32 v189, 2065, v174
	v_mul_hi_u32 v203, v189, s59
	v_lshrrev_b32_e32 v203, 7, v203
	v_mul_u32_u24_e32 v203, 0x810, v203
	v_sub_u32_e32 v189, v189, v203
	v_cmp_lt_u32_e32 vcc, 0, v189
	v_cmp_lt_u32_e64 s[8:9], 1, v189
	s_nop 1
	v_mov_b32_e32 v228, v120
	v_mov_b32_e32 v230, v121
	v_mov_b32_e32 v232, v122
	v_mov_b32_e32 v234, v123
	v_mov_b32_dpp v229, v72 row_shr:1 row_mask:0xf bank_mask:0xf bound_ctrl:1
	v_mov_b32_dpp v231, v73 row_shr:1 row_mask:0xf bank_mask:0xf bound_ctrl:1
	v_mov_b32_dpp v233, v74 row_shr:1 row_mask:0xf bank_mask:0xf bound_ctrl:1
	v_mov_b32_dpp v235, v75 row_shr:1 row_mask:0xf bank_mask:0xf bound_ctrl:1
	v_cndmask_b32_e64 v228, 0, v228, vcc
	v_cndmask_b32_e64 v229, 0, v229, s[8:9]
	v_cndmask_b32_e64 v230, 0, v230, vcc
	v_cndmask_b32_e64 v231, 0, v231, s[8:9]
	v_cndmask_b32_e64 v232, 0, v232, vcc
	v_cndmask_b32_e64 v233, 0, v233, s[8:9]
	v_cndmask_b32_e64 v234, 0, v234, vcc
	v_cndmask_b32_e64 v235, 0, v235, s[8:9]
	v_fma_f32 v236, v229, v128, v152
	v_fma_f32 v237, v231, v129, v153
	v_fma_f32 v238, v233, v130, v154
	v_fma_f32 v239, v235, v131, v155
	v_fmac_f32_e32 v236, v228, v136
	v_fmac_f32_e32 v237, v230, v137
	v_fmac_f32_e32 v238, v232, v138
	v_fmac_f32_e32 v239, v234, v139
	v_fmac_f32_e32 v236, v104, v144
	v_fmac_f32_e32 v237, v105, v145
	v_fmac_f32_e32 v238, v106, v146
	v_fmac_f32_e32 v239, v107, v147
	v_mov_b32_e32 v228, v112
	v_mov_b32_e32 v230, v113
	v_mov_b32_e32 v232, v114
	v_mov_b32_e32 v234, v115
	v_mov_b32_dpp v229, v64 row_shr:1 row_mask:0xf bank_mask:0xf bound_ctrl:1
	v_mov_b32_dpp v231, v65 row_shr:1 row_mask:0xf bank_mask:0xf bound_ctrl:1
	v_mov_b32_dpp v233, v66 row_shr:1 row_mask:0xf bank_mask:0xf bound_ctrl:1
	v_mov_b32_dpp v235, v67 row_shr:1 row_mask:0xf bank_mask:0xf bound_ctrl:1
	v_cndmask_b32_e64 v228, 0, v228, vcc
	v_cndmask_b32_e64 v229, 0, v229, s[8:9]
	v_cndmask_b32_e64 v230, 0, v230, vcc
	v_cndmask_b32_e64 v231, 0, v231, s[8:9]
	v_cndmask_b32_e64 v232, 0, v232, vcc
	v_cndmask_b32_e64 v233, 0, v233, s[8:9]
	v_cndmask_b32_e64 v234, 0, v234, vcc
	v_cndmask_b32_e64 v235, 0, v235, s[8:9]
	v_fma_f32 v240, v229, v132, v156
	v_fma_f32 v241, v231, v133, v157
	v_fma_f32 v242, v233, v134, v158
	v_fma_f32 v243, v235, v135, v159
	v_fmac_f32_e32 v240, v228, v140
	v_fmac_f32_e32 v241, v230, v141
	v_fmac_f32_e32 v242, v232, v142
	v_fmac_f32_e32 v243, v234, v143
	v_fmac_f32_e32 v240, v96, v148
	v_fmac_f32_e32 v241, v97, v149
	v_fmac_f32_e32 v242, v98, v150
	v_fmac_f32_e32 v243, v99, v151
	v_mov_b32_e32 v228, 0xbdd2d3e8
	v_mul_f32_e32 v244, v236, v236
	v_mul_f32_e32 v245, v237, v237
	v_mul_f32_e32 v246, v238, v238
	v_mul_f32_e32 v247, v239, v239
	v_fmaak_f32 v244, v244, v228, 0xc0135761
	v_fmaak_f32 v245, v245, v228, 0xc0135761
	v_fmaak_f32 v246, v246, v228, 0xc0135761
	v_fmaak_f32 v247, v247, v228, 0xc0135761
	v_mul_f32_e32 v244, v236, v244
	v_mul_f32_e32 v245, v237, v245
	v_mul_f32_e32 v246, v238, v246
	v_mul_f32_e32 v247, v239, v247
	v_exp_f32_e32 v244, v244
	v_exp_f32_e32 v245, v245
	v_exp_f32_e32 v246, v246
	v_exp_f32_e32 v247, v247
	v_add_f32_e32 v244, 1.0, v244
	v_add_f32_e32 v245, 1.0, v245
	v_add_f32_e32 v246, 1.0, v246
	v_add_f32_e32 v247, 1.0, v247
	v_rcp_f32_e32 v244, v244
	v_rcp_f32_e32 v245, v245
	v_rcp_f32_e32 v246, v246
	v_rcp_f32_e32 v247, v247
	v_mul_f32_e32 v244, v236, v244
	v_mul_f32_e32 v245, v237, v245
	v_mul_f32_e32 v246, v238, v246
	v_mul_f32_e32 v247, v239, v247
	v_mul_f32_e32 v248, v240, v244
	v_mul_f32_e32 v249, v241, v245
	v_mul_f32_e32 v250, v242, v246
	v_mul_f32_e32 v251, v243, v247
	v_mov_b32_e32 v180, v210
	v_mov_b32_e32 v181, v211
	v_cvt_pk_bf16_f32 v182, v248, v249
	v_cvt_pk_bf16_f32 v183, v250, v251
	v_add_u32_e32 v252, 1, v174
	v_mad_i64_i32 v[226:227], vcc, v252, s79, v[190:191]
	v_cmp_lt_u32_e64 s[8:9], 0, v219
	v_cmp_gt_i32_e32 vcc, s58, v252
	s_nop 1
	s_and_b64 vcc, vcc, s[8:9]
	s_and_saveexec_b64 s[10:11], vcc
	global_store_dwordx4 v[226:227], v[180:183], off sc1
	s_mov_b64 exec, s[10:11]
	v_add_u32_e32 v189, 2066, v174
	v_mul_hi_u32 v203, v189, s59
	v_lshrrev_b32_e32 v203, 7, v203
	v_mul_u32_u24_e32 v203, 0x810, v203
	v_sub_u32_e32 v189, v189, v203
	v_cmp_lt_u32_e32 vcc, 0, v189
	v_cmp_lt_u32_e64 s[8:9], 1, v189
	s_nop 1
	v_mov_b32_e32 v228, v104
	v_mov_b32_e32 v230, v105
	v_mov_b32_e32 v232, v106
	v_mov_b32_e32 v234, v107
	v_mov_b32_e32 v229, v120
	v_mov_b32_e32 v231, v121
	v_mov_b32_e32 v233, v122
	v_mov_b32_e32 v235, v123
	v_cndmask_b32_e64 v228, 0, v228, vcc
	v_cndmask_b32_e64 v229, 0, v229, s[8:9]
	v_cndmask_b32_e64 v230, 0, v230, vcc
	v_cndmask_b32_e64 v231, 0, v231, s[8:9]
	v_cndmask_b32_e64 v232, 0, v232, vcc
	v_cndmask_b32_e64 v233, 0, v233, s[8:9]
	v_cndmask_b32_e64 v234, 0, v234, vcc
	v_cndmask_b32_e64 v235, 0, v235, s[8:9]
	v_fma_f32 v236, v229, v128, v152
	v_fma_f32 v237, v231, v129, v153
	v_fma_f32 v238, v233, v130, v154
	v_fma_f32 v239, v235, v131, v155
	v_fmac_f32_e32 v236, v228, v136
	v_fmac_f32_e32 v237, v230, v137
	v_fmac_f32_e32 v238, v232, v138
	v_fmac_f32_e32 v239, v234, v139
	v_fmac_f32_e32 v236, v88, v144
	v_fmac_f32_e32 v237, v89, v145
	v_fmac_f32_e32 v238, v90, v146
	v_fmac_f32_e32 v239, v91, v147
	v_mov_b32_e32 v228, v96
	v_mov_b32_e32 v230, v97
	v_mov_b32_e32 v232, v98
	v_mov_b32_e32 v234, v99
	v_mov_b32_e32 v229, v112
	v_mov_b32_e32 v231, v113
	v_mov_b32_e32 v233, v114
	v_mov_b32_e32 v235, v115
	v_cndmask_b32_e64 v228, 0, v228, vcc
	v_cndmask_b32_e64 v229, 0, v229, s[8:9]
	v_cndmask_b32_e64 v230, 0, v230, vcc
	v_cndmask_b32_e64 v231, 0, v231, s[8:9]
	v_cndmask_b32_e64 v232, 0, v232, vcc
	v_cndmask_b32_e64 v233, 0, v233, s[8:9]
	v_cndmask_b32_e64 v234, 0, v234, vcc
	v_cndmask_b32_e64 v235, 0, v235, s[8:9]
	v_fma_f32 v240, v229, v132, v156
	v_fma_f32 v241, v231, v133, v157
	v_fma_f32 v242, v233, v134, v158
	v_fma_f32 v243, v235, v135, v159
	v_fmac_f32_e32 v240, v228, v140
	v_fmac_f32_e32 v241, v230, v141
	v_fmac_f32_e32 v242, v232, v142
	v_fmac_f32_e32 v243, v234, v143
	v_fmac_f32_e32 v240, v80, v148
	v_fmac_f32_e32 v241, v81, v149
	v_fmac_f32_e32 v242, v82, v150
	v_fmac_f32_e32 v243, v83, v151
	v_mov_b32_e32 v228, 0xbdd2d3e8
	v_mul_f32_e32 v244, v236, v236
	v_mul_f32_e32 v245, v237, v237
	v_mul_f32_e32 v246, v238, v238
	v_mul_f32_e32 v247, v239, v239
	v_fmaak_f32 v244, v244, v228, 0xc0135761
	v_fmaak_f32 v245, v245, v228, 0xc0135761
	v_fmaak_f32 v246, v246, v228, 0xc0135761
	v_fmaak_f32 v247, v247, v228, 0xc0135761
	v_mul_f32_e32 v244, v236, v244
	v_mul_f32_e32 v245, v237, v245
	v_mul_f32_e32 v246, v238, v246
	v_mul_f32_e32 v247, v239, v247
	v_exp_f32_e32 v244, v244
	v_exp_f32_e32 v245, v245
	v_exp_f32_e32 v246, v246
	v_exp_f32_e32 v247, v247
	v_add_f32_e32 v244, 1.0, v244
	v_add_f32_e32 v245, 1.0, v245
	v_add_f32_e32 v246, 1.0, v246
	v_add_f32_e32 v247, 1.0, v247
	v_rcp_f32_e32 v244, v244
	v_rcp_f32_e32 v245, v245
	v_rcp_f32_e32 v246, v246
	v_rcp_f32_e32 v247, v247
	v_mul_f32_e32 v244, v236, v244
	v_mul_f32_e32 v245, v237, v245
	v_mul_f32_e32 v246, v238, v246
	v_mul_f32_e32 v247, v239, v247
	v_mul_f32_e32 v248, v240, v244
	v_mul_f32_e32 v249, v241, v245
	v_mul_f32_e32 v250, v242, v246
	v_mul_f32_e32 v251, v243, v247
	v_mov_b32_e32 v180, v212
	v_mov_b32_e32 v181, v213
	v_cvt_pk_bf16_f32 v182, v248, v249
	v_cvt_pk_bf16_f32 v183, v250, v251
	v_add_u32_e32 v252, 2, v174
	v_mad_i64_i32 v[226:227], vcc, v252, s79, v[190:191]
	v_cmp_gt_i32_e32 vcc, s58, v252
	s_nop 1
	s_and_saveexec_b64 s[10:11], vcc
	global_store_dwordx4 v[226:227], v[180:183], off sc1
	s_mov_b64 exec, s[10:11]
	v_add_u32_e32 v189, 2067, v174
	v_mul_hi_u32 v203, v189, s59
	v_lshrrev_b32_e32 v203, 7, v203
	v_mul_u32_u24_e32 v203, 0x810, v203
	v_sub_u32_e32 v189, v189, v203
	v_cmp_lt_u32_e32 vcc, 0, v189
	v_cmp_lt_u32_e64 s[8:9], 1, v189
	s_nop 1
	v_mov_b32_e32 v228, v88
	v_mov_b32_e32 v230, v89
	v_mov_b32_e32 v232, v90
	v_mov_b32_e32 v234, v91
	v_mov_b32_e32 v229, v104
	v_mov_b32_e32 v231, v105
	v_mov_b32_e32 v233, v106
	v_mov_b32_e32 v235, v107
	v_cndmask_b32_e64 v228, 0, v228, vcc
	v_cndmask_b32_e64 v229, 0, v229, s[8:9]
	v_cndmask_b32_e64 v230, 0, v230, vcc
	v_cndmask_b32_e64 v231, 0, v231, s[8:9]
	v_cndmask_b32_e64 v232, 0, v232, vcc
	v_cndmask_b32_e64 v233, 0, v233, s[8:9]
	v_cndmask_b32_e64 v234, 0, v234, vcc
	v_cndmask_b32_e64 v235, 0, v235, s[8:9]
	v_fma_f32 v236, v229, v128, v152
	v_fma_f32 v237, v231, v129, v153
	v_fma_f32 v238, v233, v130, v154
	v_fma_f32 v239, v235, v131, v155
	v_fmac_f32_e32 v236, v228, v136
	v_fmac_f32_e32 v237, v230, v137
	v_fmac_f32_e32 v238, v232, v138
	v_fmac_f32_e32 v239, v234, v139
	v_fmac_f32_e32 v236, v72, v144
	v_fmac_f32_e32 v237, v73, v145
	v_fmac_f32_e32 v238, v74, v146
	v_fmac_f32_e32 v239, v75, v147
	v_mov_b32_e32 v228, v80
	v_mov_b32_e32 v230, v81
	v_mov_b32_e32 v232, v82
	v_mov_b32_e32 v234, v83
	v_mov_b32_e32 v229, v96
	v_mov_b32_e32 v231, v97
	v_mov_b32_e32 v233, v98
	v_mov_b32_e32 v235, v99
	v_cndmask_b32_e64 v228, 0, v228, vcc
	v_cndmask_b32_e64 v229, 0, v229, s[8:9]
	v_cndmask_b32_e64 v230, 0, v230, vcc
	v_cndmask_b32_e64 v231, 0, v231, s[8:9]
	v_cndmask_b32_e64 v232, 0, v232, vcc
	v_cndmask_b32_e64 v233, 0, v233, s[8:9]
	v_cndmask_b32_e64 v234, 0, v234, vcc
	v_cndmask_b32_e64 v235, 0, v235, s[8:9]
	v_fma_f32 v240, v229, v132, v156
	v_fma_f32 v241, v231, v133, v157
	v_fma_f32 v242, v233, v134, v158
	v_fma_f32 v243, v235, v135, v159
	v_fmac_f32_e32 v240, v228, v140
	v_fmac_f32_e32 v241, v230, v141
	v_fmac_f32_e32 v242, v232, v142
	v_fmac_f32_e32 v243, v234, v143
	v_fmac_f32_e32 v240, v64, v148
	v_fmac_f32_e32 v241, v65, v149
	v_fmac_f32_e32 v242, v66, v150
	v_fmac_f32_e32 v243, v67, v151
	v_mov_b32_e32 v228, 0xbdd2d3e8
	v_mul_f32_e32 v244, v236, v236
	v_mul_f32_e32 v245, v237, v237
	v_mul_f32_e32 v246, v238, v238
	v_mul_f32_e32 v247, v239, v239
	v_fmaak_f32 v244, v244, v228, 0xc0135761
	v_fmaak_f32 v245, v245, v228, 0xc0135761
	v_fmaak_f32 v246, v246, v228, 0xc0135761
	v_fmaak_f32 v247, v247, v228, 0xc0135761
	v_mul_f32_e32 v244, v236, v244
	v_mul_f32_e32 v245, v237, v245
	v_mul_f32_e32 v246, v238, v246
	v_mul_f32_e32 v247, v239, v247
	v_exp_f32_e32 v244, v244
	v_exp_f32_e32 v245, v245
	v_exp_f32_e32 v246, v246
	v_exp_f32_e32 v247, v247
	v_add_f32_e32 v244, 1.0, v244
	v_add_f32_e32 v245, 1.0, v245
	v_add_f32_e32 v246, 1.0, v246
	v_add_f32_e32 v247, 1.0, v247
	v_rcp_f32_e32 v244, v244
	v_rcp_f32_e32 v245, v245
	v_rcp_f32_e32 v246, v246
	v_rcp_f32_e32 v247, v247
	v_mul_f32_e32 v244, v236, v244
	v_mul_f32_e32 v245, v237, v245
	v_mul_f32_e32 v246, v238, v246
	v_mul_f32_e32 v247, v239, v247
	v_mul_f32_e32 v248, v240, v244
	v_mul_f32_e32 v249, v241, v245
	v_mul_f32_e32 v250, v242, v246
	v_mul_f32_e32 v251, v243, v247
	v_mov_b32_e32 v180, v214
	v_mov_b32_e32 v181, v215
	v_cvt_pk_bf16_f32 v182, v248, v249
	v_cvt_pk_bf16_f32 v183, v250, v251
	v_add_u32_e32 v252, 3, v174
	v_mad_i64_i32 v[226:227], vcc, v252, s79, v[190:191]
	v_cmp_gt_i32_e32 vcc, s58, v252
	s_nop 1
	s_and_saveexec_b64 s[10:11], vcc
	global_store_dwordx4 v[226:227], v[180:183], off sc1
	s_mov_b64 exec, s[10:11]
	v_add_u32_e32 v189, 2128, v174
	v_mul_hi_u32 v203, v189, s59
	v_lshrrev_b32_e32 v203, 7, v203
	v_mul_u32_u24_e32 v203, 0x810, v203
	v_sub_u32_e32 v189, v189, v203
	v_cmp_lt_u32_e32 vcc, 0, v189
	v_cmp_lt_u32_e64 s[8:9], 1, v189
	s_nop 1
	v_mov_b32_dpp v228, v72 row_ror:1 row_mask:0xf bank_mask:0xf
	v_mov_b32_dpp v230, v73 row_ror:1 row_mask:0xf bank_mask:0xf
	v_mov_b32_dpp v232, v74 row_ror:1 row_mask:0xf bank_mask:0xf
	v_mov_b32_dpp v234, v75 row_ror:1 row_mask:0xf bank_mask:0xf
	v_mov_b32_dpp v228, v12 row_shr:1 row_mask:0xf bank_mask:0xf
	v_mov_b32_dpp v230, v13 row_shr:1 row_mask:0xf bank_mask:0xf
	v_mov_b32_dpp v232, v14 row_shr:1 row_mask:0xf bank_mask:0xf
	v_mov_b32_dpp v234, v15 row_shr:1 row_mask:0xf bank_mask:0xf
	v_mov_b32_dpp v229, v88 row_ror:1 row_mask:0xf bank_mask:0xf
	v_mov_b32_dpp v231, v89 row_ror:1 row_mask:0xf bank_mask:0xf
	v_mov_b32_dpp v233, v90 row_ror:1 row_mask:0xf bank_mask:0xf
	v_mov_b32_dpp v235, v91 row_ror:1 row_mask:0xf bank_mask:0xf
	v_mov_b32_dpp v229, v24 row_shr:1 row_mask:0xf bank_mask:0xf
	v_mov_b32_dpp v231, v25 row_shr:1 row_mask:0xf bank_mask:0xf
	v_mov_b32_dpp v233, v26 row_shr:1 row_mask:0xf bank_mask:0xf
	v_mov_b32_dpp v235, v27 row_shr:1 row_mask:0xf bank_mask:0xf
	v_cndmask_b32_e64 v228, 0, v228, vcc
	v_cndmask_b32_e64 v229, 0, v229, s[8:9]
	v_cndmask_b32_e64 v230, 0, v230, vcc
	v_cndmask_b32_e64 v231, 0, v231, s[8:9]
	v_cndmask_b32_e64 v232, 0, v232, vcc
	v_cndmask_b32_e64 v233, 0, v233, s[8:9]
	v_cndmask_b32_e64 v234, 0, v234, vcc
	v_cndmask_b32_e64 v235, 0, v235, s[8:9]
	v_fma_f32 v236, v229, v128, v152
	v_fma_f32 v237, v231, v129, v153
	v_fma_f32 v238, v233, v130, v154
	v_fma_f32 v239, v235, v131, v155
	v_fmac_f32_e32 v236, v228, v136
	v_fmac_f32_e32 v237, v230, v137
	v_fmac_f32_e32 v238, v232, v138
	v_fmac_f32_e32 v239, v234, v139
	v_fmac_f32_e32 v236, v56, v144
	v_fmac_f32_e32 v237, v57, v145
	v_fmac_f32_e32 v238, v58, v146
	v_fmac_f32_e32 v239, v59, v147
	v_mov_b32_dpp v228, v64 row_ror:1 row_mask:0xf bank_mask:0xf
	v_mov_b32_dpp v230, v65 row_ror:1 row_mask:0xf bank_mask:0xf
	v_mov_b32_dpp v232, v66 row_ror:1 row_mask:0xf bank_mask:0xf
	v_mov_b32_dpp v234, v67 row_ror:1 row_mask:0xf bank_mask:0xf
	v_mov_b32_dpp v228, v0 row_shr:1 row_mask:0xf bank_mask:0xf
	v_mov_b32_dpp v230, v1 row_shr:1 row_mask:0xf bank_mask:0xf
	v_mov_b32_dpp v232, v2 row_shr:1 row_mask:0xf bank_mask:0xf
	v_mov_b32_dpp v234, v3 row_shr:1 row_mask:0xf bank_mask:0xf
	v_mov_b32_dpp v229, v80 row_ror:1 row_mask:0xf bank_mask:0xf
	v_mov_b32_dpp v231, v81 row_ror:1 row_mask:0xf bank_mask:0xf
	v_mov_b32_dpp v233, v82 row_ror:1 row_mask:0xf bank_mask:0xf
	v_mov_b32_dpp v235, v83 row_ror:1 row_mask:0xf bank_mask:0xf
	v_mov_b32_dpp v229, v16 row_shr:1 row_mask:0xf bank_mask:0xf
	v_mov_b32_dpp v231, v17 row_shr:1 row_mask:0xf bank_mask:0xf
	v_mov_b32_dpp v233, v18 row_shr:1 row_mask:0xf bank_mask:0xf
	v_mov_b32_dpp v235, v19 row_shr:1 row_mask:0xf bank_mask:0xf
	v_cndmask_b32_e64 v228, 0, v228, vcc
	v_cndmask_b32_e64 v229, 0, v229, s[8:9]
	v_cndmask_b32_e64 v230, 0, v230, vcc
	v_cndmask_b32_e64 v231, 0, v231, s[8:9]
	v_cndmask_b32_e64 v232, 0, v232, vcc
	v_cndmask_b32_e64 v233, 0, v233, s[8:9]
	v_cndmask_b32_e64 v234, 0, v234, vcc
	v_cndmask_b32_e64 v235, 0, v235, s[8:9]
	v_fma_f32 v240, v229, v132, v156
	v_fma_f32 v241, v231, v133, v157
	v_fma_f32 v242, v233, v134, v158
	v_fma_f32 v243, v235, v135, v159
	v_fmac_f32_e32 v240, v228, v140
	v_fmac_f32_e32 v241, v230, v141
	v_fmac_f32_e32 v242, v232, v142
	v_fmac_f32_e32 v243, v234, v143
	v_fmac_f32_e32 v240, v48, v148
	v_fmac_f32_e32 v241, v49, v149
	v_fmac_f32_e32 v242, v50, v150
	v_fmac_f32_e32 v243, v51, v151
	v_mov_b32_e32 v228, 0xbdd2d3e8
	v_mul_f32_e32 v244, v236, v236
	v_mul_f32_e32 v245, v237, v237
	v_mul_f32_e32 v246, v238, v238
	v_mul_f32_e32 v247, v239, v239
	v_fmaak_f32 v244, v244, v228, 0xc0135761
	v_fmaak_f32 v245, v245, v228, 0xc0135761
	v_fmaak_f32 v246, v246, v228, 0xc0135761
	v_fmaak_f32 v247, v247, v228, 0xc0135761
	v_mul_f32_e32 v244, v236, v244
	v_mul_f32_e32 v245, v237, v245
	v_mul_f32_e32 v246, v238, v246
	v_mul_f32_e32 v247, v239, v247
	v_exp_f32_e32 v244, v244
	v_exp_f32_e32 v245, v245
	v_exp_f32_e32 v246, v246
	v_exp_f32_e32 v247, v247
	v_add_f32_e32 v244, 1.0, v244
	v_add_f32_e32 v245, 1.0, v245
	v_add_f32_e32 v246, 1.0, v246
	v_add_f32_e32 v247, 1.0, v247
	v_rcp_f32_e32 v244, v244
	v_rcp_f32_e32 v245, v245
	v_rcp_f32_e32 v246, v246
	v_rcp_f32_e32 v247, v247
	v_mul_f32_e32 v244, v236, v244
	v_mul_f32_e32 v245, v237, v245
	v_mul_f32_e32 v246, v238, v246
	v_mul_f32_e32 v247, v239, v247
	v_mul_f32_e32 v248, v240, v244
	v_mul_f32_e32 v249, v241, v245
	v_mul_f32_e32 v250, v242, v246
	v_mul_f32_e32 v251, v243, v247
	v_mov_b32_e32 v180, v216
	v_mov_b32_e32 v181, v217
	v_cvt_pk_bf16_f32 v182, v248, v249
	v_cvt_pk_bf16_f32 v183, v250, v251
	v_add_u32_e32 v252, 64, v174
	v_mad_i64_i32 v[226:227], vcc, v252, s79, v[190:191]
	v_cmp_gt_i32_e32 vcc, s58, v252
	s_nop 1
	s_and_saveexec_b64 s[10:11], vcc
	global_store_dwordx4 v[226:227], v[180:183], off sc1
	s_mov_b64 exec, s[10:11]
	v_add_u32_e32 v189, 2129, v174
	v_mul_hi_u32 v203, v189, s59
	v_lshrrev_b32_e32 v203, 7, v203
	v_mul_u32_u24_e32 v203, 0x810, v203
	v_sub_u32_e32 v189, v189, v203
	v_cmp_lt_u32_e32 vcc, 0, v189
	v_cmp_lt_u32_e64 s[8:9], 1, v189
	s_nop 1
	v_mov_b32_e32 v228, v56
	v_mov_b32_e32 v230, v57
	v_mov_b32_e32 v232, v58
	v_mov_b32_e32 v234, v59
	v_mov_b32_dpp v229, v72 row_ror:1 row_mask:0xf bank_mask:0xf
	v_mov_b32_dpp v231, v73 row_ror:1 row_mask:0xf bank_mask:0xf
	v_mov_b32_dpp v233, v74 row_ror:1 row_mask:0xf bank_mask:0xf
	v_mov_b32_dpp v235, v75 row_ror:1 row_mask:0xf bank_mask:0xf
	v_mov_b32_dpp v229, v12 row_shr:1 row_mask:0xf bank_mask:0xf
	v_mov_b32_dpp v231, v13 row_shr:1 row_mask:0xf bank_mask:0xf
	v_mov_b32_dpp v233, v14 row_shr:1 row_mask:0xf bank_mask:0xf
	v_mov_b32_dpp v235, v15 row_shr:1 row_mask:0xf bank_mask:0xf
	v_cndmask_b32_e64 v228, 0, v228, vcc
	v_cndmask_b32_e64 v229, 0, v229, s[8:9]
	v_cndmask_b32_e64 v230, 0, v230, vcc
	v_cndmask_b32_e64 v231, 0, v231, s[8:9]
	v_cndmask_b32_e64 v232, 0, v232, vcc
	v_cndmask_b32_e64 v233, 0, v233, s[8:9]
	v_cndmask_b32_e64 v234, 0, v234, vcc
	v_cndmask_b32_e64 v235, 0, v235, s[8:9]
	v_fma_f32 v236, v229, v128, v152
	v_fma_f32 v237, v231, v129, v153
	v_fma_f32 v238, v233, v130, v154
	v_fma_f32 v239, v235, v131, v155
	v_fmac_f32_e32 v236, v228, v136
	v_fmac_f32_e32 v237, v230, v137
	v_fmac_f32_e32 v238, v232, v138
	v_fmac_f32_e32 v239, v234, v139
	v_fmac_f32_e32 v236, v40, v144
	v_fmac_f32_e32 v237, v41, v145
	v_fmac_f32_e32 v238, v42, v146
	v_fmac_f32_e32 v239, v43, v147
	v_mov_b32_e32 v228, v48
	v_mov_b32_e32 v230, v49
	v_mov_b32_e32 v232, v50
	v_mov_b32_e32 v234, v51
	v_mov_b32_dpp v229, v64 row_ror:1 row_mask:0xf bank_mask:0xf
	v_mov_b32_dpp v231, v65 row_ror:1 row_mask:0xf bank_mask:0xf
	v_mov_b32_dpp v233, v66 row_ror:1 row_mask:0xf bank_mask:0xf
	v_mov_b32_dpp v235, v67 row_ror:1 row_mask:0xf bank_mask:0xf
	v_mov_b32_dpp v229, v0 row_shr:1 row_mask:0xf bank_mask:0xf
	v_mov_b32_dpp v231, v1 row_shr:1 row_mask:0xf bank_mask:0xf
	v_mov_b32_dpp v233, v2 row_shr:1 row_mask:0xf bank_mask:0xf
	v_mov_b32_dpp v235, v3 row_shr:1 row_mask:0xf bank_mask:0xf
	v_cndmask_b32_e64 v228, 0, v228, vcc
	v_cndmask_b32_e64 v229, 0, v229, s[8:9]
	v_cndmask_b32_e64 v230, 0, v230, vcc
	v_cndmask_b32_e64 v231, 0, v231, s[8:9]
	v_cndmask_b32_e64 v232, 0, v232, vcc
	v_cndmask_b32_e64 v233, 0, v233, s[8:9]
	v_cndmask_b32_e64 v234, 0, v234, vcc
	v_cndmask_b32_e64 v235, 0, v235, s[8:9]
	v_fma_f32 v240, v229, v132, v156
	v_fma_f32 v241, v231, v133, v157
	v_fma_f32 v242, v233, v134, v158
	v_fma_f32 v243, v235, v135, v159
	v_fmac_f32_e32 v240, v228, v140
	v_fmac_f32_e32 v241, v230, v141
	v_fmac_f32_e32 v242, v232, v142
	v_fmac_f32_e32 v243, v234, v143
	v_fmac_f32_e32 v240, v32, v148
	v_fmac_f32_e32 v241, v33, v149
	v_fmac_f32_e32 v242, v34, v150
	v_fmac_f32_e32 v243, v35, v151
	v_mov_b32_e32 v228, 0xbdd2d3e8
	v_mul_f32_e32 v244, v236, v236
	v_mul_f32_e32 v245, v237, v237
	v_mul_f32_e32 v246, v238, v238
	v_mul_f32_e32 v247, v239, v239
	v_fmaak_f32 v244, v244, v228, 0xc0135761
	v_fmaak_f32 v245, v245, v228, 0xc0135761
	v_fmaak_f32 v246, v246, v228, 0xc0135761
	v_fmaak_f32 v247, v247, v228, 0xc0135761
	v_mul_f32_e32 v244, v236, v244
	v_mul_f32_e32 v245, v237, v245
	v_mul_f32_e32 v246, v238, v246
	v_mul_f32_e32 v247, v239, v247
	v_exp_f32_e32 v244, v244
	v_exp_f32_e32 v245, v245
	v_exp_f32_e32 v246, v246
	v_exp_f32_e32 v247, v247
	v_add_f32_e32 v244, 1.0, v244
	v_add_f32_e32 v245, 1.0, v245
	v_add_f32_e32 v246, 1.0, v246
	v_add_f32_e32 v247, 1.0, v247
	v_rcp_f32_e32 v244, v244
	v_rcp_f32_e32 v245, v245
	v_rcp_f32_e32 v246, v246
	v_rcp_f32_e32 v247, v247
	v_mul_f32_e32 v244, v236, v244
	v_mul_f32_e32 v245, v237, v245
	v_mul_f32_e32 v246, v238, v246
	v_mul_f32_e32 v247, v239, v247
	v_mul_f32_e32 v248, v240, v244
	v_mul_f32_e32 v249, v241, v245
	v_mul_f32_e32 v250, v242, v246
	v_mul_f32_e32 v251, v243, v247
	v_mov_b32_e32 v180, v220
	v_mov_b32_e32 v181, v221
	v_cvt_pk_bf16_f32 v182, v248, v249
	v_cvt_pk_bf16_f32 v183, v250, v251
	v_add_u32_e32 v252, 65, v174
	v_mad_i64_i32 v[226:227], vcc, v252, s79, v[190:191]
	v_cmp_gt_i32_e32 vcc, s58, v252
	s_nop 1
	s_and_saveexec_b64 s[10:11], vcc
	global_store_dwordx4 v[226:227], v[180:183], off sc1
	s_mov_b64 exec, s[10:11]
	v_add_u32_e32 v189, 2130, v174
	v_mul_hi_u32 v203, v189, s59
	v_lshrrev_b32_e32 v203, 7, v203
	v_mul_u32_u24_e32 v203, 0x810, v203
	v_sub_u32_e32 v189, v189, v203
	v_cmp_lt_u32_e32 vcc, 0, v189
	v_cmp_lt_u32_e64 s[8:9], 1, v189
	s_nop 1
	v_mov_b32_e32 v228, v40
	v_mov_b32_e32 v230, v41
	v_mov_b32_e32 v232, v42
	v_mov_b32_e32 v234, v43
	v_mov_b32_e32 v229, v56
	v_mov_b32_e32 v231, v57
	v_mov_b32_e32 v233, v58
	v_mov_b32_e32 v235, v59
	v_cndmask_b32_e64 v228, 0, v228, vcc
	v_cndmask_b32_e64 v229, 0, v229, s[8:9]
	v_cndmask_b32_e64 v230, 0, v230, vcc
	v_cndmask_b32_e64 v231, 0, v231, s[8:9]
	v_cndmask_b32_e64 v232, 0, v232, vcc
	v_cndmask_b32_e64 v233, 0, v233, s[8:9]
	v_cndmask_b32_e64 v234, 0, v234, vcc
	v_cndmask_b32_e64 v235, 0, v235, s[8:9]
	v_fma_f32 v236, v229, v128, v152
	v_fma_f32 v237, v231, v129, v153
	v_fma_f32 v238, v233, v130, v154
	v_fma_f32 v239, v235, v131, v155
	v_fmac_f32_e32 v236, v228, v136
	v_fmac_f32_e32 v237, v230, v137
	v_fmac_f32_e32 v238, v232, v138
	v_fmac_f32_e32 v239, v234, v139
	v_fmac_f32_e32 v236, v24, v144
	v_fmac_f32_e32 v237, v25, v145
	v_fmac_f32_e32 v238, v26, v146
	v_fmac_f32_e32 v239, v27, v147
	v_mov_b32_e32 v228, v32
	v_mov_b32_e32 v230, v33
	v_mov_b32_e32 v232, v34
	v_mov_b32_e32 v234, v35
	v_mov_b32_e32 v229, v48
	v_mov_b32_e32 v231, v49
	v_mov_b32_e32 v233, v50
	v_mov_b32_e32 v235, v51
	v_cndmask_b32_e64 v228, 0, v228, vcc
	v_cndmask_b32_e64 v229, 0, v229, s[8:9]
	v_cndmask_b32_e64 v230, 0, v230, vcc
	v_cndmask_b32_e64 v231, 0, v231, s[8:9]
	v_cndmask_b32_e64 v232, 0, v232, vcc
	v_cndmask_b32_e64 v233, 0, v233, s[8:9]
	v_cndmask_b32_e64 v234, 0, v234, vcc
	v_cndmask_b32_e64 v235, 0, v235, s[8:9]
	v_fma_f32 v240, v229, v132, v156
	v_fma_f32 v241, v231, v133, v157
	v_fma_f32 v242, v233, v134, v158
	v_fma_f32 v243, v235, v135, v159
	v_fmac_f32_e32 v240, v228, v140
	v_fmac_f32_e32 v241, v230, v141
	v_fmac_f32_e32 v242, v232, v142
	v_fmac_f32_e32 v243, v234, v143
	v_fmac_f32_e32 v240, v16, v148
	v_fmac_f32_e32 v241, v17, v149
	v_fmac_f32_e32 v242, v18, v150
	v_fmac_f32_e32 v243, v19, v151
	v_mov_b32_e32 v228, 0xbdd2d3e8
	v_mul_f32_e32 v244, v236, v236
	v_mul_f32_e32 v245, v237, v237
	v_mul_f32_e32 v246, v238, v238
	v_mul_f32_e32 v247, v239, v239
	v_fmaak_f32 v244, v244, v228, 0xc0135761
	v_fmaak_f32 v245, v245, v228, 0xc0135761
	v_fmaak_f32 v246, v246, v228, 0xc0135761
	v_fmaak_f32 v247, v247, v228, 0xc0135761
	v_mul_f32_e32 v244, v236, v244
	v_mul_f32_e32 v245, v237, v245
	v_mul_f32_e32 v246, v238, v246
	v_mul_f32_e32 v247, v239, v247
	v_exp_f32_e32 v244, v244
	v_exp_f32_e32 v245, v245
	v_exp_f32_e32 v246, v246
	v_exp_f32_e32 v247, v247
	v_add_f32_e32 v244, 1.0, v244
	v_add_f32_e32 v245, 1.0, v245
	v_add_f32_e32 v246, 1.0, v246
	v_add_f32_e32 v247, 1.0, v247
	v_rcp_f32_e32 v244, v244
	v_rcp_f32_e32 v245, v245
	v_rcp_f32_e32 v246, v246
	v_rcp_f32_e32 v247, v247
	v_mul_f32_e32 v244, v236, v244
	v_mul_f32_e32 v245, v237, v245
	v_mul_f32_e32 v246, v238, v246
	v_mul_f32_e32 v247, v239, v247
	v_mul_f32_e32 v248, v240, v244
	v_mul_f32_e32 v249, v241, v245
	v_mul_f32_e32 v250, v242, v246
	v_mul_f32_e32 v251, v243, v247
	v_mov_b32_e32 v180, v222
	v_mov_b32_e32 v181, v223
	v_cvt_pk_bf16_f32 v182, v248, v249
	v_cvt_pk_bf16_f32 v183, v250, v251
	v_add_u32_e32 v252, 66, v174
	v_mad_i64_i32 v[226:227], vcc, v252, s79, v[190:191]
	v_cmp_gt_i32_e32 vcc, s58, v252
	s_nop 1
	s_and_saveexec_b64 s[10:11], vcc
	global_store_dwordx4 v[226:227], v[180:183], off sc1
	s_mov_b64 exec, s[10:11]
	v_add_u32_e32 v189, 2131, v174
	v_mul_hi_u32 v203, v189, s59
	v_lshrrev_b32_e32 v203, 7, v203
	v_mul_u32_u24_e32 v203, 0x810, v203
	v_sub_u32_e32 v189, v189, v203
	v_cmp_lt_u32_e32 vcc, 0, v189
	v_cmp_lt_u32_e64 s[8:9], 1, v189
	s_nop 1
	v_mov_b32_e32 v228, v24
	v_mov_b32_e32 v230, v25
	v_mov_b32_e32 v232, v26
	v_mov_b32_e32 v234, v27
	v_mov_b32_e32 v229, v40
	v_mov_b32_e32 v231, v41
	v_mov_b32_e32 v233, v42
	v_mov_b32_e32 v235, v43
	v_cndmask_b32_e64 v228, 0, v228, vcc
	v_cndmask_b32_e64 v229, 0, v229, s[8:9]
	v_cndmask_b32_e64 v230, 0, v230, vcc
	v_cndmask_b32_e64 v231, 0, v231, s[8:9]
	v_cndmask_b32_e64 v232, 0, v232, vcc
	v_cndmask_b32_e64 v233, 0, v233, s[8:9]
	v_cndmask_b32_e64 v234, 0, v234, vcc
	v_cndmask_b32_e64 v235, 0, v235, s[8:9]
	v_fma_f32 v236, v229, v128, v152
	v_fma_f32 v237, v231, v129, v153
	v_fma_f32 v238, v233, v130, v154
	v_fma_f32 v239, v235, v131, v155
	v_fmac_f32_e32 v236, v228, v136
	v_fmac_f32_e32 v237, v230, v137
	v_fmac_f32_e32 v238, v232, v138
	v_fmac_f32_e32 v239, v234, v139
	v_fmac_f32_e32 v236, v12, v144
	v_fmac_f32_e32 v237, v13, v145
	v_fmac_f32_e32 v238, v14, v146
	v_fmac_f32_e32 v239, v15, v147
	v_mov_b32_e32 v228, v16
	v_mov_b32_e32 v230, v17
	v_mov_b32_e32 v232, v18
	v_mov_b32_e32 v234, v19
	v_mov_b32_e32 v229, v32
	v_mov_b32_e32 v231, v33
	v_mov_b32_e32 v233, v34
	v_mov_b32_e32 v235, v35
	v_cndmask_b32_e64 v228, 0, v228, vcc
	v_cndmask_b32_e64 v229, 0, v229, s[8:9]
	v_cndmask_b32_e64 v230, 0, v230, vcc
	v_cndmask_b32_e64 v231, 0, v231, s[8:9]
	v_cndmask_b32_e64 v232, 0, v232, vcc
	v_cndmask_b32_e64 v233, 0, v233, s[8:9]
	v_cndmask_b32_e64 v234, 0, v234, vcc
	v_cndmask_b32_e64 v235, 0, v235, s[8:9]
	v_fma_f32 v240, v229, v132, v156
	v_fma_f32 v241, v231, v133, v157
	v_fma_f32 v242, v233, v134, v158
	v_fma_f32 v243, v235, v135, v159
	v_fmac_f32_e32 v240, v228, v140
	v_fmac_f32_e32 v241, v230, v141
	v_fmac_f32_e32 v242, v232, v142
	v_fmac_f32_e32 v243, v234, v143
	v_fmac_f32_e32 v240, v0, v148
	v_fmac_f32_e32 v241, v1, v149
	v_fmac_f32_e32 v242, v2, v150
	v_fmac_f32_e32 v243, v3, v151
	v_mov_b32_e32 v228, 0xbdd2d3e8
	v_mul_f32_e32 v244, v236, v236
	v_mul_f32_e32 v245, v237, v237
	v_mul_f32_e32 v246, v238, v238
	v_mul_f32_e32 v247, v239, v239
	v_fmaak_f32 v244, v244, v228, 0xc0135761
	v_fmaak_f32 v245, v245, v228, 0xc0135761
	v_fmaak_f32 v246, v246, v228, 0xc0135761
	v_fmaak_f32 v247, v247, v228, 0xc0135761
	v_mul_f32_e32 v244, v236, v244
	v_mul_f32_e32 v245, v237, v245
	v_mul_f32_e32 v246, v238, v246
	v_mul_f32_e32 v247, v239, v247
	v_exp_f32_e32 v244, v244
	v_exp_f32_e32 v245, v245
	v_exp_f32_e32 v246, v246
	v_exp_f32_e32 v247, v247
	v_add_f32_e32 v244, 1.0, v244
	v_add_f32_e32 v245, 1.0, v245
	v_add_f32_e32 v246, 1.0, v246
	v_add_f32_e32 v247, 1.0, v247
	v_rcp_f32_e32 v244, v244
	v_rcp_f32_e32 v245, v245
	v_rcp_f32_e32 v246, v246
	v_rcp_f32_e32 v247, v247
	v_mul_f32_e32 v244, v236, v244
	v_mul_f32_e32 v245, v237, v245
	v_mul_f32_e32 v246, v238, v246
	v_mul_f32_e32 v247, v239, v247
	v_mul_f32_e32 v248, v240, v244
	v_mul_f32_e32 v249, v241, v245
	v_mul_f32_e32 v250, v242, v246
	v_mul_f32_e32 v251, v243, v247
	v_mov_b32_e32 v180, v224
	v_mov_b32_e32 v181, v225
	v_cvt_pk_bf16_f32 v182, v248, v249
	v_cvt_pk_bf16_f32 v183, v250, v251
	v_add_u32_e32 v252, 67, v174
	v_mad_i64_i32 v[226:227], vcc, v252, s79, v[190:191]
	v_cmp_gt_i32_e32 vcc, s58, v252
	s_nop 1
	s_and_saveexec_b64 s[10:11], vcc
	global_store_dwordx4 v[226:227], v[180:183], off sc1
	s_mov_b64 exec, s[10:11]
